# v43 + epilogue de-serialisation of the residual-add epilogues (8 loads in flight) on top of the full-line column remap
# baseline (speedup 1.0000x reference)
.LBB0_998:
	v_lshl_add_u32 v146, s76, 8, v1
	v_lshl_or_b32 v148, s73, 8, v163
	v_ashrrev_i32_e32 v147, 31, v146
	v_ashrrev_i32_e32 v149, 31, v148
	v_lshlrev_b64 v[150:151], 12, v[146:147]
	v_lshl_add_u64 v[150:151], s[64:65], 0, v[150:151]
	v_lshlrev_b64 v[148:149], 1, v[148:149]
	v_lshl_add_u64 v[150:151], v[150:151], 0, v[148:149]
	v_mov_b32_e32 v245, 0
	v_mov_b32_e32 v244, 0x10000
	v_lshl_add_u64 v[230:231], v[244:245], 0, v[150:151]
	v_mov_b32_e32 v244, 0x20000
	v_lshl_add_u64 v[232:233], v[244:245], 0, v[150:151]
	v_mov_b32_e32 v244, 0x30000
	v_lshl_add_u64 v[234:235], v[244:245], 0, v[150:151]
	v_mov_b32_e32 v244, 0x80000
	v_lshl_add_u64 v[236:237], v[244:245], 0, v[150:151]
	v_mov_b32_e32 v244, 0x90000
	v_lshl_add_u64 v[238:239], v[244:245], 0, v[150:151]
	v_mov_b32_e32 v244, 0xa0000
	v_lshl_add_u64 v[240:241], v[244:245], 0, v[150:151]
	v_mov_b32_e32 v244, 0xb0000
	v_lshl_add_u64 v[242:243], v[244:245], 0, v[150:151]
	global_load_dwordx4 v[146:149], v[150:151], off
	global_load_dwordx4 v[152:155], v[150:151], off offset:64
	global_load_dwordx4 v[156:159], v[230:231], off
	global_load_dwordx4 v[168:171], v[230:231], off offset:64
	global_load_dwordx4 v[172:175], v[232:233], off
	global_load_dwordx4 v[176:179], v[232:233], off offset:64
	global_load_dwordx4 v[180:183], v[234:235], off
	global_load_dwordx4 v[184:187], v[234:235], off offset:64
	s_waitcnt vmcnt(7)
	v_cvt_f32_f16_e32 v160, v146
	v_cvt_f32_f16_sdwa v161, v146 dst_sel:DWORD dst_unused:UNUSED_PAD src0_sel:WORD_1
	v_cvt_f32_f16_e32 v188, v147
	v_cvt_f32_f16_sdwa v189, v147 dst_sel:DWORD dst_unused:UNUSED_PAD src0_sel:WORD_1
	v_cvt_f32_f16_e32 v190, v148
	v_cvt_f32_f16_sdwa v191, v148 dst_sel:DWORD dst_unused:UNUSED_PAD src0_sel:WORD_1
	v_cvt_f32_f16_e32 v228, v149
	v_cvt_f32_f16_sdwa v229, v149 dst_sel:DWORD dst_unused:UNUSED_PAD src0_sel:WORD_1
	global_load_dwordx4 v[146:149], v[236:237], off
	v_pk_add_f32 v[126:127], v[160:161], v[126:127]
	v_pk_add_f32 v[128:129], v[188:189], v[128:129]
	v_pk_add_f32 v[122:123], v[190:191], v[122:123]
	v_pk_add_f32 v[124:125], v[228:229], v[124:125]
	v_cvt_pk_f16_f32 v125, v124, v125
	v_cvt_pk_f16_f32 v124, v122, v123
	v_cvt_pk_f16_f32 v123, v128, v129
	v_cvt_pk_f16_f32 v122, v126, v127
	global_store_dwordx4 v[150:151], v[122:125], off
	s_waitcnt vmcnt(8)
	v_cvt_f32_f16_e32 v160, v152
	v_cvt_f32_f16_sdwa v161, v152 dst_sel:DWORD dst_unused:UNUSED_PAD src0_sel:WORD_1
	v_cvt_f32_f16_e32 v188, v153
	v_cvt_f32_f16_sdwa v189, v153 dst_sel:DWORD dst_unused:UNUSED_PAD src0_sel:WORD_1
	v_cvt_f32_f16_e32 v190, v154
	v_cvt_f32_f16_sdwa v191, v154 dst_sel:DWORD dst_unused:UNUSED_PAD src0_sel:WORD_1
	v_cvt_f32_f16_e32 v228, v155
	v_cvt_f32_f16_sdwa v229, v155 dst_sel:DWORD dst_unused:UNUSED_PAD src0_sel:WORD_1
	global_load_dwordx4 v[152:155], v[236:237], off offset:64
	v_pk_add_f32 v[118:119], v[160:161], v[118:119]
	v_pk_add_f32 v[120:121], v[188:189], v[120:121]
	v_pk_add_f32 v[114:115], v[190:191], v[114:115]
	v_pk_add_f32 v[116:117], v[228:229], v[116:117]
	v_cvt_pk_f16_f32 v117, v116, v117
	v_cvt_pk_f16_f32 v116, v114, v115
	v_cvt_pk_f16_f32 v115, v120, v121
	v_cvt_pk_f16_f32 v114, v118, v119
	global_store_dwordx4 v[150:151], v[114:117], off offset:64
	s_waitcnt vmcnt(9)
	v_cvt_f32_f16_e32 v160, v156
	v_cvt_f32_f16_sdwa v161, v156 dst_sel:DWORD dst_unused:UNUSED_PAD src0_sel:WORD_1
	v_cvt_f32_f16_e32 v188, v157
	v_cvt_f32_f16_sdwa v189, v157 dst_sel:DWORD dst_unused:UNUSED_PAD src0_sel:WORD_1
	v_cvt_f32_f16_e32 v190, v158
	v_cvt_f32_f16_sdwa v191, v158 dst_sel:DWORD dst_unused:UNUSED_PAD src0_sel:WORD_1
	v_cvt_f32_f16_e32 v228, v159
	v_cvt_f32_f16_sdwa v229, v159 dst_sel:DWORD dst_unused:UNUSED_PAD src0_sel:WORD_1
	global_load_dwordx4 v[156:159], v[238:239], off
	v_pk_add_f32 v[110:111], v[160:161], v[110:111]
	v_pk_add_f32 v[112:113], v[188:189], v[112:113]
	v_pk_add_f32 v[106:107], v[190:191], v[106:107]
	v_pk_add_f32 v[108:109], v[228:229], v[108:109]
	v_cvt_pk_f16_f32 v109, v108, v109
	v_cvt_pk_f16_f32 v108, v106, v107
	v_cvt_pk_f16_f32 v107, v112, v113
	v_cvt_pk_f16_f32 v106, v110, v111
	global_store_dwordx4 v[230:231], v[106:109], off
	s_waitcnt vmcnt(10)
	v_cvt_f32_f16_e32 v160, v168
	v_cvt_f32_f16_sdwa v161, v168 dst_sel:DWORD dst_unused:UNUSED_PAD src0_sel:WORD_1
	v_cvt_f32_f16_e32 v188, v169
	v_cvt_f32_f16_sdwa v189, v169 dst_sel:DWORD dst_unused:UNUSED_PAD src0_sel:WORD_1
	v_cvt_f32_f16_e32 v190, v170
	v_cvt_f32_f16_sdwa v191, v170 dst_sel:DWORD dst_unused:UNUSED_PAD src0_sel:WORD_1
	v_cvt_f32_f16_e32 v228, v171
	v_cvt_f32_f16_sdwa v229, v171 dst_sel:DWORD dst_unused:UNUSED_PAD src0_sel:WORD_1
	global_load_dwordx4 v[168:171], v[238:239], off offset:64
	v_pk_add_f32 v[102:103], v[160:161], v[102:103]
	v_pk_add_f32 v[104:105], v[188:189], v[104:105]
	v_pk_add_f32 v[98:99], v[190:191], v[98:99]
	v_pk_add_f32 v[100:101], v[228:229], v[100:101]
	v_cvt_pk_f16_f32 v101, v100, v101
	v_cvt_pk_f16_f32 v100, v98, v99
	v_cvt_pk_f16_f32 v99, v104, v105
	v_cvt_pk_f16_f32 v98, v102, v103
	global_store_dwordx4 v[230:231], v[98:101], off offset:64
	s_waitcnt vmcnt(11)
	v_cvt_f32_f16_e32 v160, v172
	v_cvt_f32_f16_sdwa v161, v172 dst_sel:DWORD dst_unused:UNUSED_PAD src0_sel:WORD_1
	v_cvt_f32_f16_e32 v188, v173
	v_cvt_f32_f16_sdwa v189, v173 dst_sel:DWORD dst_unused:UNUSED_PAD src0_sel:WORD_1
	v_cvt_f32_f16_e32 v190, v174
	v_cvt_f32_f16_sdwa v191, v174 dst_sel:DWORD dst_unused:UNUSED_PAD src0_sel:WORD_1
	v_cvt_f32_f16_e32 v228, v175
	v_cvt_f32_f16_sdwa v229, v175 dst_sel:DWORD dst_unused:UNUSED_PAD src0_sel:WORD_1
	global_load_dwordx4 v[172:175], v[240:241], off
	v_pk_add_f32 v[94:95], v[160:161], v[94:95]
	v_pk_add_f32 v[96:97], v[188:189], v[96:97]
	v_pk_add_f32 v[90:91], v[190:191], v[90:91]
	v_pk_add_f32 v[92:93], v[228:229], v[92:93]
	v_cvt_pk_f16_f32 v93, v92, v93
	v_cvt_pk_f16_f32 v92, v90, v91
	v_cvt_pk_f16_f32 v91, v96, v97
	v_cvt_pk_f16_f32 v90, v94, v95
	global_store_dwordx4 v[232:233], v[90:93], off
	s_waitcnt vmcnt(12)
	v_cvt_f32_f16_e32 v160, v176
	v_cvt_f32_f16_sdwa v161, v176 dst_sel:DWORD dst_unused:UNUSED_PAD src0_sel:WORD_1
	v_cvt_f32_f16_e32 v188, v177
	v_cvt_f32_f16_sdwa v189, v177 dst_sel:DWORD dst_unused:UNUSED_PAD src0_sel:WORD_1
	v_cvt_f32_f16_e32 v190, v178
	v_cvt_f32_f16_sdwa v191, v178 dst_sel:DWORD dst_unused:UNUSED_PAD src0_sel:WORD_1
	v_cvt_f32_f16_e32 v228, v179
	v_cvt_f32_f16_sdwa v229, v179 dst_sel:DWORD dst_unused:UNUSED_PAD src0_sel:WORD_1
	global_load_dwordx4 v[176:179], v[240:241], off offset:64
	v_pk_add_f32 v[86:87], v[160:161], v[86:87]
	v_pk_add_f32 v[88:89], v[188:189], v[88:89]
	v_pk_add_f32 v[82:83], v[190:191], v[82:83]
	v_pk_add_f32 v[84:85], v[228:229], v[84:85]
	v_cvt_pk_f16_f32 v85, v84, v85
	v_cvt_pk_f16_f32 v84, v82, v83
	v_cvt_pk_f16_f32 v83, v88, v89
	v_cvt_pk_f16_f32 v82, v86, v87
	global_store_dwordx4 v[232:233], v[82:85], off offset:64
	s_waitcnt vmcnt(13)
	v_cvt_f32_f16_e32 v160, v180
	v_cvt_f32_f16_sdwa v161, v180 dst_sel:DWORD dst_unused:UNUSED_PAD src0_sel:WORD_1
	v_cvt_f32_f16_e32 v188, v181
	v_cvt_f32_f16_sdwa v189, v181 dst_sel:DWORD dst_unused:UNUSED_PAD src0_sel:WORD_1
	v_cvt_f32_f16_e32 v190, v182
	v_cvt_f32_f16_sdwa v191, v182 dst_sel:DWORD dst_unused:UNUSED_PAD src0_sel:WORD_1
	v_cvt_f32_f16_e32 v228, v183
	v_cvt_f32_f16_sdwa v229, v183 dst_sel:DWORD dst_unused:UNUSED_PAD src0_sel:WORD_1
	global_load_dwordx4 v[180:183], v[242:243], off
	v_pk_add_f32 v[78:79], v[160:161], v[78:79]
	v_pk_add_f32 v[80:81], v[188:189], v[80:81]
	v_pk_add_f32 v[74:75], v[190:191], v[74:75]
	v_pk_add_f32 v[76:77], v[228:229], v[76:77]
	v_cvt_pk_f16_f32 v77, v76, v77
	v_cvt_pk_f16_f32 v76, v74, v75
	v_cvt_pk_f16_f32 v75, v80, v81
	v_cvt_pk_f16_f32 v74, v78, v79
	global_store_dwordx4 v[234:235], v[74:77], off
	s_waitcnt vmcnt(14)
	v_cvt_f32_f16_e32 v160, v184
	v_cvt_f32_f16_sdwa v161, v184 dst_sel:DWORD dst_unused:UNUSED_PAD src0_sel:WORD_1
	v_cvt_f32_f16_e32 v188, v185
	v_cvt_f32_f16_sdwa v189, v185 dst_sel:DWORD dst_unused:UNUSED_PAD src0_sel:WORD_1
	v_cvt_f32_f16_e32 v190, v186
	v_cvt_f32_f16_sdwa v191, v186 dst_sel:DWORD dst_unused:UNUSED_PAD src0_sel:WORD_1
	v_cvt_f32_f16_e32 v228, v187
	v_cvt_f32_f16_sdwa v229, v187 dst_sel:DWORD dst_unused:UNUSED_PAD src0_sel:WORD_1
	global_load_dwordx4 v[184:187], v[242:243], off offset:64
	v_pk_add_f32 v[70:71], v[160:161], v[70:71]
	v_pk_add_f32 v[72:73], v[188:189], v[72:73]
	v_pk_add_f32 v[66:67], v[190:191], v[66:67]
	v_pk_add_f32 v[68:69], v[228:229], v[68:69]
	v_cvt_pk_f16_f32 v69, v68, v69
	v_cvt_pk_f16_f32 v68, v66, v67
	v_cvt_pk_f16_f32 v67, v72, v73
	v_cvt_pk_f16_f32 v66, v70, v71
	global_store_dwordx4 v[234:235], v[66:69], off offset:64
	s_waitcnt vmcnt(15)
	v_cvt_f32_f16_e32 v160, v146
	v_cvt_f32_f16_sdwa v161, v146 dst_sel:DWORD dst_unused:UNUSED_PAD src0_sel:WORD_1
	v_cvt_f32_f16_e32 v188, v147
	v_cvt_f32_f16_sdwa v189, v147 dst_sel:DWORD dst_unused:UNUSED_PAD src0_sel:WORD_1
	v_cvt_f32_f16_e32 v190, v148
	v_cvt_f32_f16_sdwa v191, v148 dst_sel:DWORD dst_unused:UNUSED_PAD src0_sel:WORD_1
	v_cvt_f32_f16_e32 v228, v149
	v_cvt_f32_f16_sdwa v229, v149 dst_sel:DWORD dst_unused:UNUSED_PAD src0_sel:WORD_1
	v_pk_add_f32 v[62:63], v[160:161], v[62:63]
	v_pk_add_f32 v[64:65], v[188:189], v[64:65]
	v_pk_add_f32 v[58:59], v[190:191], v[58:59]
	v_pk_add_f32 v[60:61], v[228:229], v[60:61]
	v_cvt_pk_f16_f32 v61, v60, v61
	v_cvt_pk_f16_f32 v60, v58, v59
	v_cvt_pk_f16_f32 v59, v64, v65
	v_cvt_pk_f16_f32 v58, v62, v63
	global_store_dwordx4 v[236:237], v[58:61], off
	s_waitcnt vmcnt(14)
	v_cvt_f32_f16_e32 v160, v152
	v_cvt_f32_f16_sdwa v161, v152 dst_sel:DWORD dst_unused:UNUSED_PAD src0_sel:WORD_1
	v_cvt_f32_f16_e32 v188, v153
	v_cvt_f32_f16_sdwa v189, v153 dst_sel:DWORD dst_unused:UNUSED_PAD src0_sel:WORD_1
	v_cvt_f32_f16_e32 v190, v154
	v_cvt_f32_f16_sdwa v191, v154 dst_sel:DWORD dst_unused:UNUSED_PAD src0_sel:WORD_1
	v_cvt_f32_f16_e32 v228, v155
	v_cvt_f32_f16_sdwa v229, v155 dst_sel:DWORD dst_unused:UNUSED_PAD src0_sel:WORD_1
	v_pk_add_f32 v[54:55], v[160:161], v[54:55]
	v_pk_add_f32 v[56:57], v[188:189], v[56:57]
	v_pk_add_f32 v[50:51], v[190:191], v[50:51]
	v_pk_add_f32 v[52:53], v[228:229], v[52:53]
	v_cvt_pk_f16_f32 v53, v52, v53
	v_cvt_pk_f16_f32 v52, v50, v51
	v_cvt_pk_f16_f32 v51, v56, v57
	v_cvt_pk_f16_f32 v50, v54, v55
	global_store_dwordx4 v[236:237], v[50:53], off offset:64
	s_waitcnt vmcnt(13)
	v_cvt_f32_f16_e32 v160, v156
	v_cvt_f32_f16_sdwa v161, v156 dst_sel:DWORD dst_unused:UNUSED_PAD src0_sel:WORD_1
	v_cvt_f32_f16_e32 v188, v157
	v_cvt_f32_f16_sdwa v189, v157 dst_sel:DWORD dst_unused:UNUSED_PAD src0_sel:WORD_1
	v_cvt_f32_f16_e32 v190, v158
	v_cvt_f32_f16_sdwa v191, v158 dst_sel:DWORD dst_unused:UNUSED_PAD src0_sel:WORD_1
	v_cvt_f32_f16_e32 v228, v159
	v_cvt_f32_f16_sdwa v229, v159 dst_sel:DWORD dst_unused:UNUSED_PAD src0_sel:WORD_1
	v_pk_add_f32 v[46:47], v[160:161], v[46:47]
	v_pk_add_f32 v[48:49], v[188:189], v[48:49]
	v_pk_add_f32 v[42:43], v[190:191], v[42:43]
	v_pk_add_f32 v[44:45], v[228:229], v[44:45]
	v_cvt_pk_f16_f32 v45, v44, v45
	v_cvt_pk_f16_f32 v44, v42, v43
	v_cvt_pk_f16_f32 v43, v48, v49
	v_cvt_pk_f16_f32 v42, v46, v47
	global_store_dwordx4 v[238:239], v[42:45], off
	s_waitcnt vmcnt(12)
	v_cvt_f32_f16_e32 v160, v168
	v_cvt_f32_f16_sdwa v161, v168 dst_sel:DWORD dst_unused:UNUSED_PAD src0_sel:WORD_1
	v_cvt_f32_f16_e32 v188, v169
	v_cvt_f32_f16_sdwa v189, v169 dst_sel:DWORD dst_unused:UNUSED_PAD src0_sel:WORD_1
	v_cvt_f32_f16_e32 v190, v170
	v_cvt_f32_f16_sdwa v191, v170 dst_sel:DWORD dst_unused:UNUSED_PAD src0_sel:WORD_1
	v_cvt_f32_f16_e32 v228, v171
	v_cvt_f32_f16_sdwa v229, v171 dst_sel:DWORD dst_unused:UNUSED_PAD src0_sel:WORD_1
	v_pk_add_f32 v[38:39], v[160:161], v[38:39]
	v_pk_add_f32 v[40:41], v[188:189], v[40:41]
	v_pk_add_f32 v[34:35], v[190:191], v[34:35]
	v_pk_add_f32 v[36:37], v[228:229], v[36:37]
	v_cvt_pk_f16_f32 v37, v36, v37
	v_cvt_pk_f16_f32 v36, v34, v35
	v_cvt_pk_f16_f32 v35, v40, v41
	v_cvt_pk_f16_f32 v34, v38, v39
	global_store_dwordx4 v[238:239], v[34:37], off offset:64
	s_waitcnt vmcnt(11)
	v_cvt_f32_f16_e32 v160, v172
	v_cvt_f32_f16_sdwa v161, v172 dst_sel:DWORD dst_unused:UNUSED_PAD src0_sel:WORD_1
	v_cvt_f32_f16_e32 v188, v173
	v_cvt_f32_f16_sdwa v189, v173 dst_sel:DWORD dst_unused:UNUSED_PAD src0_sel:WORD_1
	v_cvt_f32_f16_e32 v190, v174
	v_cvt_f32_f16_sdwa v191, v174 dst_sel:DWORD dst_unused:UNUSED_PAD src0_sel:WORD_1
	v_cvt_f32_f16_e32 v228, v175
	v_cvt_f32_f16_sdwa v229, v175 dst_sel:DWORD dst_unused:UNUSED_PAD src0_sel:WORD_1
	v_pk_add_f32 v[30:31], v[160:161], v[30:31]
	v_pk_add_f32 v[32:33], v[188:189], v[32:33]
	v_pk_add_f32 v[26:27], v[190:191], v[26:27]
	v_pk_add_f32 v[28:29], v[228:229], v[28:29]
	v_cvt_pk_f16_f32 v29, v28, v29
	v_cvt_pk_f16_f32 v28, v26, v27
	v_cvt_pk_f16_f32 v27, v32, v33
	v_cvt_pk_f16_f32 v26, v30, v31
	global_store_dwordx4 v[240:241], v[26:29], off
	s_waitcnt vmcnt(10)
	v_cvt_f32_f16_e32 v160, v176
	v_cvt_f32_f16_sdwa v161, v176 dst_sel:DWORD dst_unused:UNUSED_PAD src0_sel:WORD_1
	v_cvt_f32_f16_e32 v188, v177
	v_cvt_f32_f16_sdwa v189, v177 dst_sel:DWORD dst_unused:UNUSED_PAD src0_sel:WORD_1
	v_cvt_f32_f16_e32 v190, v178
	v_cvt_f32_f16_sdwa v191, v178 dst_sel:DWORD dst_unused:UNUSED_PAD src0_sel:WORD_1
	v_cvt_f32_f16_e32 v228, v179
	v_cvt_f32_f16_sdwa v229, v179 dst_sel:DWORD dst_unused:UNUSED_PAD src0_sel:WORD_1
	v_pk_add_f32 v[22:23], v[160:161], v[22:23]
	v_pk_add_f32 v[24:25], v[188:189], v[24:25]
	v_pk_add_f32 v[18:19], v[190:191], v[18:19]
	v_pk_add_f32 v[20:21], v[228:229], v[20:21]
	v_cvt_pk_f16_f32 v21, v20, v21
	v_cvt_pk_f16_f32 v20, v18, v19
	v_cvt_pk_f16_f32 v19, v24, v25
	v_cvt_pk_f16_f32 v18, v22, v23
	global_store_dwordx4 v[240:241], v[18:21], off offset:64
	s_waitcnt vmcnt(9)
	v_cvt_f32_f16_e32 v160, v180
	v_cvt_f32_f16_sdwa v161, v180 dst_sel:DWORD dst_unused:UNUSED_PAD src0_sel:WORD_1
	v_cvt_f32_f16_e32 v188, v181
	v_cvt_f32_f16_sdwa v189, v181 dst_sel:DWORD dst_unused:UNUSED_PAD src0_sel:WORD_1
	v_cvt_f32_f16_e32 v190, v182
	v_cvt_f32_f16_sdwa v191, v182 dst_sel:DWORD dst_unused:UNUSED_PAD src0_sel:WORD_1
	v_cvt_f32_f16_e32 v228, v183
	v_cvt_f32_f16_sdwa v229, v183 dst_sel:DWORD dst_unused:UNUSED_PAD src0_sel:WORD_1
	v_pk_add_f32 v[14:15], v[160:161], v[14:15]
	v_pk_add_f32 v[16:17], v[188:189], v[16:17]
	v_pk_add_f32 v[10:11], v[190:191], v[10:11]
	v_pk_add_f32 v[12:13], v[228:229], v[12:13]
	v_cvt_pk_f16_f32 v13, v12, v13
	v_cvt_pk_f16_f32 v12, v10, v11
	v_cvt_pk_f16_f32 v11, v16, v17
	v_cvt_pk_f16_f32 v10, v14, v15
	global_store_dwordx4 v[242:243], v[10:13], off
	s_waitcnt vmcnt(8)
	v_cvt_f32_f16_e32 v160, v184
	v_cvt_f32_f16_sdwa v161, v184 dst_sel:DWORD dst_unused:UNUSED_PAD src0_sel:WORD_1
	v_cvt_f32_f16_e32 v188, v185
	v_cvt_f32_f16_sdwa v189, v185 dst_sel:DWORD dst_unused:UNUSED_PAD src0_sel:WORD_1
	v_cvt_f32_f16_e32 v190, v186
	v_cvt_f32_f16_sdwa v191, v186 dst_sel:DWORD dst_unused:UNUSED_PAD src0_sel:WORD_1
	v_cvt_f32_f16_e32 v228, v187
	v_cvt_f32_f16_sdwa v229, v187 dst_sel:DWORD dst_unused:UNUSED_PAD src0_sel:WORD_1
	v_pk_add_f32 v[6:7], v[160:161], v[6:7]
	v_pk_add_f32 v[8:9], v[188:189], v[8:9]
	v_pk_add_f32 v[2:3], v[190:191], v[2:3]
	v_pk_add_f32 v[4:5], v[228:229], v[4:5]
	v_cvt_pk_f16_f32 v5, v4, v5
	v_cvt_pk_f16_f32 v4, v2, v3
	v_cvt_pk_f16_f32 v3, v8, v9
	v_cvt_pk_f16_f32 v2, v6, v7
	global_store_dwordx4 v[242:243], v[2:5], off offset:64
	s_mov_b64 s[0:1], -1
	s_andn2_b64 vcc, exec, s[2:3]
	s_cbranch_vccnz .LBB0_987
	s_andn2_b64 vcc, exec, s[6:7]
	s_cbranch_vccnz .LBB0_986
	s_barrier
	s_branch .LBB0_986

.LBB0_1240:
	v_lshl_add_u32 v146, s75, 8, v1
	v_lshl_or_b32 v148, s86, 8, v163
	v_ashrrev_i32_e32 v147, 31, v146
	v_ashrrev_i32_e32 v149, 31, v148
	v_lshlrev_b64 v[150:151], 12, v[146:147]
	v_lshl_add_u64 v[150:151], s[64:65], 0, v[150:151]
	v_lshlrev_b64 v[148:149], 1, v[148:149]
	v_lshl_add_u64 v[150:151], v[150:151], 0, v[148:149]
	v_mov_b32_e32 v245, 0
	v_mov_b32_e32 v244, 0x10000
	v_lshl_add_u64 v[230:231], v[244:245], 0, v[150:151]
	v_mov_b32_e32 v244, 0x20000
	v_lshl_add_u64 v[232:233], v[244:245], 0, v[150:151]
	v_mov_b32_e32 v244, 0x30000
	v_lshl_add_u64 v[234:235], v[244:245], 0, v[150:151]
	v_mov_b32_e32 v244, 0x80000
	v_lshl_add_u64 v[236:237], v[244:245], 0, v[150:151]
	v_mov_b32_e32 v244, 0x90000
	v_lshl_add_u64 v[238:239], v[244:245], 0, v[150:151]
	v_mov_b32_e32 v244, 0xa0000
	v_lshl_add_u64 v[240:241], v[244:245], 0, v[150:151]
	v_mov_b32_e32 v244, 0xb0000
	v_lshl_add_u64 v[242:243], v[244:245], 0, v[150:151]
	global_load_dwordx4 v[146:149], v[150:151], off
	global_load_dwordx4 v[152:155], v[150:151], off offset:64
	global_load_dwordx4 v[156:159], v[230:231], off
	global_load_dwordx4 v[168:171], v[230:231], off offset:64
	global_load_dwordx4 v[172:175], v[232:233], off
	global_load_dwordx4 v[176:179], v[232:233], off offset:64
	global_load_dwordx4 v[180:183], v[234:235], off
	global_load_dwordx4 v[184:187], v[234:235], off offset:64
	s_waitcnt vmcnt(7)
	v_cvt_f32_f16_e32 v160, v146
	v_cvt_f32_f16_sdwa v161, v146 dst_sel:DWORD dst_unused:UNUSED_PAD src0_sel:WORD_1
	v_cvt_f32_f16_e32 v188, v147
	v_cvt_f32_f16_sdwa v189, v147 dst_sel:DWORD dst_unused:UNUSED_PAD src0_sel:WORD_1
	v_cvt_f32_f16_e32 v190, v148
	v_cvt_f32_f16_sdwa v191, v148 dst_sel:DWORD dst_unused:UNUSED_PAD src0_sel:WORD_1
	v_cvt_f32_f16_e32 v228, v149
	v_cvt_f32_f16_sdwa v229, v149 dst_sel:DWORD dst_unused:UNUSED_PAD src0_sel:WORD_1
	global_load_dwordx4 v[146:149], v[236:237], off
	v_pk_fma_f32 v[126:127], v[126:127], 0.5, v[160:161] op_sel_hi:[1,0,1]
	v_pk_fma_f32 v[128:129], v[128:129], 0.5, v[188:189] op_sel_hi:[1,0,1]
	v_pk_fma_f32 v[122:123], v[122:123], 0.5, v[190:191] op_sel_hi:[1,0,1]
	v_pk_fma_f32 v[124:125], v[124:125], 0.5, v[228:229] op_sel_hi:[1,0,1]
	v_cvt_pk_f16_f32 v125, v124, v125
	v_cvt_pk_f16_f32 v124, v122, v123
	v_cvt_pk_f16_f32 v123, v128, v129
	v_cvt_pk_f16_f32 v122, v126, v127
	global_store_dwordx4 v[150:151], v[122:125], off
	s_waitcnt vmcnt(8)
	v_cvt_f32_f16_e32 v160, v152
	v_cvt_f32_f16_sdwa v161, v152 dst_sel:DWORD dst_unused:UNUSED_PAD src0_sel:WORD_1
	v_cvt_f32_f16_e32 v188, v153
	v_cvt_f32_f16_sdwa v189, v153 dst_sel:DWORD dst_unused:UNUSED_PAD src0_sel:WORD_1
	v_cvt_f32_f16_e32 v190, v154
	v_cvt_f32_f16_sdwa v191, v154 dst_sel:DWORD dst_unused:UNUSED_PAD src0_sel:WORD_1
	v_cvt_f32_f16_e32 v228, v155
	v_cvt_f32_f16_sdwa v229, v155 dst_sel:DWORD dst_unused:UNUSED_PAD src0_sel:WORD_1
	global_load_dwordx4 v[152:155], v[236:237], off offset:64
	v_pk_fma_f32 v[118:119], v[118:119], 0.5, v[160:161] op_sel_hi:[1,0,1]
	v_pk_fma_f32 v[120:121], v[120:121], 0.5, v[188:189] op_sel_hi:[1,0,1]
	v_pk_fma_f32 v[114:115], v[114:115], 0.5, v[190:191] op_sel_hi:[1,0,1]
	v_pk_fma_f32 v[116:117], v[116:117], 0.5, v[228:229] op_sel_hi:[1,0,1]
	v_cvt_pk_f16_f32 v117, v116, v117
	v_cvt_pk_f16_f32 v116, v114, v115
	v_cvt_pk_f16_f32 v115, v120, v121
	v_cvt_pk_f16_f32 v114, v118, v119
	global_store_dwordx4 v[150:151], v[114:117], off offset:64
	s_waitcnt vmcnt(9)
	v_cvt_f32_f16_e32 v160, v156
	v_cvt_f32_f16_sdwa v161, v156 dst_sel:DWORD dst_unused:UNUSED_PAD src0_sel:WORD_1
	v_cvt_f32_f16_e32 v188, v157
	v_cvt_f32_f16_sdwa v189, v157 dst_sel:DWORD dst_unused:UNUSED_PAD src0_sel:WORD_1
	v_cvt_f32_f16_e32 v190, v158
	v_cvt_f32_f16_sdwa v191, v158 dst_sel:DWORD dst_unused:UNUSED_PAD src0_sel:WORD_1
	v_cvt_f32_f16_e32 v228, v159
	v_cvt_f32_f16_sdwa v229, v159 dst_sel:DWORD dst_unused:UNUSED_PAD src0_sel:WORD_1
	global_load_dwordx4 v[156:159], v[238:239], off
	v_pk_fma_f32 v[110:111], v[110:111], 0.5, v[160:161] op_sel_hi:[1,0,1]
	v_pk_fma_f32 v[112:113], v[112:113], 0.5, v[188:189] op_sel_hi:[1,0,1]
	v_pk_fma_f32 v[106:107], v[106:107], 0.5, v[190:191] op_sel_hi:[1,0,1]
	v_pk_fma_f32 v[108:109], v[108:109], 0.5, v[228:229] op_sel_hi:[1,0,1]
	v_cvt_pk_f16_f32 v109, v108, v109
	v_cvt_pk_f16_f32 v108, v106, v107
	v_cvt_pk_f16_f32 v107, v112, v113
	v_cvt_pk_f16_f32 v106, v110, v111
	global_store_dwordx4 v[230:231], v[106:109], off
	s_waitcnt vmcnt(10)
	v_cvt_f32_f16_e32 v160, v168
	v_cvt_f32_f16_sdwa v161, v168 dst_sel:DWORD dst_unused:UNUSED_PAD src0_sel:WORD_1
	v_cvt_f32_f16_e32 v188, v169
	v_cvt_f32_f16_sdwa v189, v169 dst_sel:DWORD dst_unused:UNUSED_PAD src0_sel:WORD_1
	v_cvt_f32_f16_e32 v190, v170
	v_cvt_f32_f16_sdwa v191, v170 dst_sel:DWORD dst_unused:UNUSED_PAD src0_sel:WORD_1
	v_cvt_f32_f16_e32 v228, v171
	v_cvt_f32_f16_sdwa v229, v171 dst_sel:DWORD dst_unused:UNUSED_PAD src0_sel:WORD_1
	global_load_dwordx4 v[168:171], v[238:239], off offset:64
	v_pk_fma_f32 v[102:103], v[102:103], 0.5, v[160:161] op_sel_hi:[1,0,1]
	v_pk_fma_f32 v[104:105], v[104:105], 0.5, v[188:189] op_sel_hi:[1,0,1]
	v_pk_fma_f32 v[98:99], v[98:99], 0.5, v[190:191] op_sel_hi:[1,0,1]
	v_pk_fma_f32 v[100:101], v[100:101], 0.5, v[228:229] op_sel_hi:[1,0,1]
	v_cvt_pk_f16_f32 v101, v100, v101
	v_cvt_pk_f16_f32 v100, v98, v99
	v_cvt_pk_f16_f32 v99, v104, v105
	v_cvt_pk_f16_f32 v98, v102, v103
	global_store_dwordx4 v[230:231], v[98:101], off offset:64
	s_waitcnt vmcnt(11)
	v_cvt_f32_f16_e32 v160, v172
	v_cvt_f32_f16_sdwa v161, v172 dst_sel:DWORD dst_unused:UNUSED_PAD src0_sel:WORD_1
	v_cvt_f32_f16_e32 v188, v173
	v_cvt_f32_f16_sdwa v189, v173 dst_sel:DWORD dst_unused:UNUSED_PAD src0_sel:WORD_1
	v_cvt_f32_f16_e32 v190, v174
	v_cvt_f32_f16_sdwa v191, v174 dst_sel:DWORD dst_unused:UNUSED_PAD src0_sel:WORD_1
	v_cvt_f32_f16_e32 v228, v175
	v_cvt_f32_f16_sdwa v229, v175 dst_sel:DWORD dst_unused:UNUSED_PAD src0_sel:WORD_1
	global_load_dwordx4 v[172:175], v[240:241], off
	v_pk_fma_f32 v[94:95], v[94:95], 0.5, v[160:161] op_sel_hi:[1,0,1]
	v_pk_fma_f32 v[96:97], v[96:97], 0.5, v[188:189] op_sel_hi:[1,0,1]
	v_pk_fma_f32 v[90:91], v[90:91], 0.5, v[190:191] op_sel_hi:[1,0,1]
	v_pk_fma_f32 v[92:93], v[92:93], 0.5, v[228:229] op_sel_hi:[1,0,1]
	v_cvt_pk_f16_f32 v93, v92, v93
	v_cvt_pk_f16_f32 v92, v90, v91
	v_cvt_pk_f16_f32 v91, v96, v97
	v_cvt_pk_f16_f32 v90, v94, v95
	global_store_dwordx4 v[232:233], v[90:93], off
	s_waitcnt vmcnt(12)
	v_cvt_f32_f16_e32 v160, v176
	v_cvt_f32_f16_sdwa v161, v176 dst_sel:DWORD dst_unused:UNUSED_PAD src0_sel:WORD_1
	v_cvt_f32_f16_e32 v188, v177
	v_cvt_f32_f16_sdwa v189, v177 dst_sel:DWORD dst_unused:UNUSED_PAD src0_sel:WORD_1
	v_cvt_f32_f16_e32 v190, v178
	v_cvt_f32_f16_sdwa v191, v178 dst_sel:DWORD dst_unused:UNUSED_PAD src0_sel:WORD_1
	v_cvt_f32_f16_e32 v228, v179
	v_cvt_f32_f16_sdwa v229, v179 dst_sel:DWORD dst_unused:UNUSED_PAD src0_sel:WORD_1
	global_load_dwordx4 v[176:179], v[240:241], off offset:64
	v_pk_fma_f32 v[86:87], v[86:87], 0.5, v[160:161] op_sel_hi:[1,0,1]
	v_pk_fma_f32 v[88:89], v[88:89], 0.5, v[188:189] op_sel_hi:[1,0,1]
	v_pk_fma_f32 v[82:83], v[82:83], 0.5, v[190:191] op_sel_hi:[1,0,1]
	v_pk_fma_f32 v[84:85], v[84:85], 0.5, v[228:229] op_sel_hi:[1,0,1]
	v_cvt_pk_f16_f32 v85, v84, v85
	v_cvt_pk_f16_f32 v84, v82, v83
	v_cvt_pk_f16_f32 v83, v88, v89
	v_cvt_pk_f16_f32 v82, v86, v87
	global_store_dwordx4 v[232:233], v[82:85], off offset:64
	s_waitcnt vmcnt(13)
	v_cvt_f32_f16_e32 v160, v180
	v_cvt_f32_f16_sdwa v161, v180 dst_sel:DWORD dst_unused:UNUSED_PAD src0_sel:WORD_1
	v_cvt_f32_f16_e32 v188, v181
	v_cvt_f32_f16_sdwa v189, v181 dst_sel:DWORD dst_unused:UNUSED_PAD src0_sel:WORD_1
	v_cvt_f32_f16_e32 v190, v182
	v_cvt_f32_f16_sdwa v191, v182 dst_sel:DWORD dst_unused:UNUSED_PAD src0_sel:WORD_1
	v_cvt_f32_f16_e32 v228, v183
	v_cvt_f32_f16_sdwa v229, v183 dst_sel:DWORD dst_unused:UNUSED_PAD src0_sel:WORD_1
	global_load_dwordx4 v[180:183], v[242:243], off
	v_pk_fma_f32 v[78:79], v[78:79], 0.5, v[160:161] op_sel_hi:[1,0,1]
	v_pk_fma_f32 v[80:81], v[80:81], 0.5, v[188:189] op_sel_hi:[1,0,1]
	v_pk_fma_f32 v[74:75], v[74:75], 0.5, v[190:191] op_sel_hi:[1,0,1]
	v_pk_fma_f32 v[76:77], v[76:77], 0.5, v[228:229] op_sel_hi:[1,0,1]
	v_cvt_pk_f16_f32 v77, v76, v77
	v_cvt_pk_f16_f32 v76, v74, v75
	v_cvt_pk_f16_f32 v75, v80, v81
	v_cvt_pk_f16_f32 v74, v78, v79
	global_store_dwordx4 v[234:235], v[74:77], off
	s_waitcnt vmcnt(14)
	v_cvt_f32_f16_e32 v160, v184
	v_cvt_f32_f16_sdwa v161, v184 dst_sel:DWORD dst_unused:UNUSED_PAD src0_sel:WORD_1
	v_cvt_f32_f16_e32 v188, v185
	v_cvt_f32_f16_sdwa v189, v185 dst_sel:DWORD dst_unused:UNUSED_PAD src0_sel:WORD_1
	v_cvt_f32_f16_e32 v190, v186
	v_cvt_f32_f16_sdwa v191, v186 dst_sel:DWORD dst_unused:UNUSED_PAD src0_sel:WORD_1
	v_cvt_f32_f16_e32 v228, v187
	v_cvt_f32_f16_sdwa v229, v187 dst_sel:DWORD dst_unused:UNUSED_PAD src0_sel:WORD_1
	global_load_dwordx4 v[184:187], v[242:243], off offset:64
	v_pk_fma_f32 v[70:71], v[70:71], 0.5, v[160:161] op_sel_hi:[1,0,1]
	v_pk_fma_f32 v[72:73], v[72:73], 0.5, v[188:189] op_sel_hi:[1,0,1]
	v_pk_fma_f32 v[66:67], v[66:67], 0.5, v[190:191] op_sel_hi:[1,0,1]
	v_pk_fma_f32 v[68:69], v[68:69], 0.5, v[228:229] op_sel_hi:[1,0,1]
	v_cvt_pk_f16_f32 v69, v68, v69
	v_cvt_pk_f16_f32 v68, v66, v67
	v_cvt_pk_f16_f32 v67, v72, v73
	v_cvt_pk_f16_f32 v66, v70, v71
	global_store_dwordx4 v[234:235], v[66:69], off offset:64
	s_waitcnt vmcnt(15)
	v_cvt_f32_f16_e32 v160, v146
	v_cvt_f32_f16_sdwa v161, v146 dst_sel:DWORD dst_unused:UNUSED_PAD src0_sel:WORD_1
	v_cvt_f32_f16_e32 v188, v147
	v_cvt_f32_f16_sdwa v189, v147 dst_sel:DWORD dst_unused:UNUSED_PAD src0_sel:WORD_1
	v_cvt_f32_f16_e32 v190, v148
	v_cvt_f32_f16_sdwa v191, v148 dst_sel:DWORD dst_unused:UNUSED_PAD src0_sel:WORD_1
	v_cvt_f32_f16_e32 v228, v149
	v_cvt_f32_f16_sdwa v229, v149 dst_sel:DWORD dst_unused:UNUSED_PAD src0_sel:WORD_1
	v_pk_fma_f32 v[62:63], v[62:63], 0.5, v[160:161] op_sel_hi:[1,0,1]
	v_pk_fma_f32 v[64:65], v[64:65], 0.5, v[188:189] op_sel_hi:[1,0,1]
	v_pk_fma_f32 v[58:59], v[58:59], 0.5, v[190:191] op_sel_hi:[1,0,1]
	v_pk_fma_f32 v[60:61], v[60:61], 0.5, v[228:229] op_sel_hi:[1,0,1]
	v_cvt_pk_f16_f32 v61, v60, v61
	v_cvt_pk_f16_f32 v60, v58, v59
	v_cvt_pk_f16_f32 v59, v64, v65
	v_cvt_pk_f16_f32 v58, v62, v63
	global_store_dwordx4 v[236:237], v[58:61], off
	s_waitcnt vmcnt(14)
	v_cvt_f32_f16_e32 v160, v152
	v_cvt_f32_f16_sdwa v161, v152 dst_sel:DWORD dst_unused:UNUSED_PAD src0_sel:WORD_1
	v_cvt_f32_f16_e32 v188, v153
	v_cvt_f32_f16_sdwa v189, v153 dst_sel:DWORD dst_unused:UNUSED_PAD src0_sel:WORD_1
	v_cvt_f32_f16_e32 v190, v154
	v_cvt_f32_f16_sdwa v191, v154 dst_sel:DWORD dst_unused:UNUSED_PAD src0_sel:WORD_1
	v_cvt_f32_f16_e32 v228, v155
	v_cvt_f32_f16_sdwa v229, v155 dst_sel:DWORD dst_unused:UNUSED_PAD src0_sel:WORD_1
	v_pk_fma_f32 v[54:55], v[54:55], 0.5, v[160:161] op_sel_hi:[1,0,1]
	v_pk_fma_f32 v[56:57], v[56:57], 0.5, v[188:189] op_sel_hi:[1,0,1]
	v_pk_fma_f32 v[50:51], v[50:51], 0.5, v[190:191] op_sel_hi:[1,0,1]
	v_pk_fma_f32 v[52:53], v[52:53], 0.5, v[228:229] op_sel_hi:[1,0,1]
	v_cvt_pk_f16_f32 v53, v52, v53
	v_cvt_pk_f16_f32 v52, v50, v51
	v_cvt_pk_f16_f32 v51, v56, v57
	v_cvt_pk_f16_f32 v50, v54, v55
	global_store_dwordx4 v[236:237], v[50:53], off offset:64
	s_waitcnt vmcnt(13)
	v_cvt_f32_f16_e32 v160, v156
	v_cvt_f32_f16_sdwa v161, v156 dst_sel:DWORD dst_unused:UNUSED_PAD src0_sel:WORD_1
	v_cvt_f32_f16_e32 v188, v157
	v_cvt_f32_f16_sdwa v189, v157 dst_sel:DWORD dst_unused:UNUSED_PAD src0_sel:WORD_1
	v_cvt_f32_f16_e32 v190, v158
	v_cvt_f32_f16_sdwa v191, v158 dst_sel:DWORD dst_unused:UNUSED_PAD src0_sel:WORD_1
	v_cvt_f32_f16_e32 v228, v159
	v_cvt_f32_f16_sdwa v229, v159 dst_sel:DWORD dst_unused:UNUSED_PAD src0_sel:WORD_1
	v_pk_fma_f32 v[46:47], v[46:47], 0.5, v[160:161] op_sel_hi:[1,0,1]
	v_pk_fma_f32 v[48:49], v[48:49], 0.5, v[188:189] op_sel_hi:[1,0,1]
	v_pk_fma_f32 v[42:43], v[42:43], 0.5, v[190:191] op_sel_hi:[1,0,1]
	v_pk_fma_f32 v[44:45], v[44:45], 0.5, v[228:229] op_sel_hi:[1,0,1]
	v_cvt_pk_f16_f32 v45, v44, v45
	v_cvt_pk_f16_f32 v44, v42, v43
	v_cvt_pk_f16_f32 v43, v48, v49
	v_cvt_pk_f16_f32 v42, v46, v47
	global_store_dwordx4 v[238:239], v[42:45], off
	s_waitcnt vmcnt(12)
	v_cvt_f32_f16_e32 v160, v168
	v_cvt_f32_f16_sdwa v161, v168 dst_sel:DWORD dst_unused:UNUSED_PAD src0_sel:WORD_1
	v_cvt_f32_f16_e32 v188, v169
	v_cvt_f32_f16_sdwa v189, v169 dst_sel:DWORD dst_unused:UNUSED_PAD src0_sel:WORD_1
	v_cvt_f32_f16_e32 v190, v170
	v_cvt_f32_f16_sdwa v191, v170 dst_sel:DWORD dst_unused:UNUSED_PAD src0_sel:WORD_1
	v_cvt_f32_f16_e32 v228, v171
	v_cvt_f32_f16_sdwa v229, v171 dst_sel:DWORD dst_unused:UNUSED_PAD src0_sel:WORD_1
	v_pk_fma_f32 v[38:39], v[38:39], 0.5, v[160:161] op_sel_hi:[1,0,1]
	v_pk_fma_f32 v[40:41], v[40:41], 0.5, v[188:189] op_sel_hi:[1,0,1]
	v_pk_fma_f32 v[34:35], v[34:35], 0.5, v[190:191] op_sel_hi:[1,0,1]
	v_pk_fma_f32 v[36:37], v[36:37], 0.5, v[228:229] op_sel_hi:[1,0,1]
	v_cvt_pk_f16_f32 v37, v36, v37
	v_cvt_pk_f16_f32 v36, v34, v35
	v_cvt_pk_f16_f32 v35, v40, v41
	v_cvt_pk_f16_f32 v34, v38, v39
	global_store_dwordx4 v[238:239], v[34:37], off offset:64
	s_waitcnt vmcnt(11)
	v_cvt_f32_f16_e32 v160, v172
	v_cvt_f32_f16_sdwa v161, v172 dst_sel:DWORD dst_unused:UNUSED_PAD src0_sel:WORD_1
	v_cvt_f32_f16_e32 v188, v173
	v_cvt_f32_f16_sdwa v189, v173 dst_sel:DWORD dst_unused:UNUSED_PAD src0_sel:WORD_1
	v_cvt_f32_f16_e32 v190, v174
	v_cvt_f32_f16_sdwa v191, v174 dst_sel:DWORD dst_unused:UNUSED_PAD src0_sel:WORD_1
	v_cvt_f32_f16_e32 v228, v175
	v_cvt_f32_f16_sdwa v229, v175 dst_sel:DWORD dst_unused:UNUSED_PAD src0_sel:WORD_1
	v_pk_fma_f32 v[30:31], v[30:31], 0.5, v[160:161] op_sel_hi:[1,0,1]
	v_pk_fma_f32 v[32:33], v[32:33], 0.5, v[188:189] op_sel_hi:[1,0,1]
	v_pk_fma_f32 v[26:27], v[26:27], 0.5, v[190:191] op_sel_hi:[1,0,1]
	v_pk_fma_f32 v[28:29], v[28:29], 0.5, v[228:229] op_sel_hi:[1,0,1]
	v_cvt_pk_f16_f32 v29, v28, v29
	v_cvt_pk_f16_f32 v28, v26, v27
	v_cvt_pk_f16_f32 v27, v32, v33
	v_cvt_pk_f16_f32 v26, v30, v31
	global_store_dwordx4 v[240:241], v[26:29], off
	s_waitcnt vmcnt(10)
	v_cvt_f32_f16_e32 v160, v176
	v_cvt_f32_f16_sdwa v161, v176 dst_sel:DWORD dst_unused:UNUSED_PAD src0_sel:WORD_1
	v_cvt_f32_f16_e32 v188, v177
	v_cvt_f32_f16_sdwa v189, v177 dst_sel:DWORD dst_unused:UNUSED_PAD src0_sel:WORD_1
	v_cvt_f32_f16_e32 v190, v178
	v_cvt_f32_f16_sdwa v191, v178 dst_sel:DWORD dst_unused:UNUSED_PAD src0_sel:WORD_1
	v_cvt_f32_f16_e32 v228, v179
	v_cvt_f32_f16_sdwa v229, v179 dst_sel:DWORD dst_unused:UNUSED_PAD src0_sel:WORD_1
	v_pk_fma_f32 v[22:23], v[22:23], 0.5, v[160:161] op_sel_hi:[1,0,1]
	v_pk_fma_f32 v[24:25], v[24:25], 0.5, v[188:189] op_sel_hi:[1,0,1]
	v_pk_fma_f32 v[18:19], v[18:19], 0.5, v[190:191] op_sel_hi:[1,0,1]
	v_pk_fma_f32 v[20:21], v[20:21], 0.5, v[228:229] op_sel_hi:[1,0,1]
	v_cvt_pk_f16_f32 v21, v20, v21
	v_cvt_pk_f16_f32 v20, v18, v19
	v_cvt_pk_f16_f32 v19, v24, v25
	v_cvt_pk_f16_f32 v18, v22, v23
	global_store_dwordx4 v[240:241], v[18:21], off offset:64
	s_waitcnt vmcnt(9)
	v_cvt_f32_f16_e32 v160, v180
	v_cvt_f32_f16_sdwa v161, v180 dst_sel:DWORD dst_unused:UNUSED_PAD src0_sel:WORD_1
	v_cvt_f32_f16_e32 v188, v181
	v_cvt_f32_f16_sdwa v189, v181 dst_sel:DWORD dst_unused:UNUSED_PAD src0_sel:WORD_1
	v_cvt_f32_f16_e32 v190, v182
	v_cvt_f32_f16_sdwa v191, v182 dst_sel:DWORD dst_unused:UNUSED_PAD src0_sel:WORD_1
	v_cvt_f32_f16_e32 v228, v183
	v_cvt_f32_f16_sdwa v229, v183 dst_sel:DWORD dst_unused:UNUSED_PAD src0_sel:WORD_1
	v_pk_fma_f32 v[14:15], v[14:15], 0.5, v[160:161] op_sel_hi:[1,0,1]
	v_pk_fma_f32 v[16:17], v[16:17], 0.5, v[188:189] op_sel_hi:[1,0,1]
	v_pk_fma_f32 v[10:11], v[10:11], 0.5, v[190:191] op_sel_hi:[1,0,1]
	v_pk_fma_f32 v[12:13], v[12:13], 0.5, v[228:229] op_sel_hi:[1,0,1]
	v_cvt_pk_f16_f32 v13, v12, v13
	v_cvt_pk_f16_f32 v12, v10, v11
	v_cvt_pk_f16_f32 v11, v16, v17
	v_cvt_pk_f16_f32 v10, v14, v15
	global_store_dwordx4 v[242:243], v[10:13], off
	s_waitcnt vmcnt(8)
	v_cvt_f32_f16_e32 v160, v184
	v_cvt_f32_f16_sdwa v161, v184 dst_sel:DWORD dst_unused:UNUSED_PAD src0_sel:WORD_1
	v_cvt_f32_f16_e32 v188, v185
	v_cvt_f32_f16_sdwa v189, v185 dst_sel:DWORD dst_unused:UNUSED_PAD src0_sel:WORD_1
	v_cvt_f32_f16_e32 v190, v186
	v_cvt_f32_f16_sdwa v191, v186 dst_sel:DWORD dst_unused:UNUSED_PAD src0_sel:WORD_1
	v_cvt_f32_f16_e32 v228, v187
	v_cvt_f32_f16_sdwa v229, v187 dst_sel:DWORD dst_unused:UNUSED_PAD src0_sel:WORD_1
	v_pk_fma_f32 v[6:7], v[6:7], 0.5, v[160:161] op_sel_hi:[1,0,1]
	v_pk_fma_f32 v[8:9], v[8:9], 0.5, v[188:189] op_sel_hi:[1,0,1]
	v_pk_fma_f32 v[2:3], v[2:3], 0.5, v[190:191] op_sel_hi:[1,0,1]
	v_pk_fma_f32 v[4:5], v[4:5], 0.5, v[228:229] op_sel_hi:[1,0,1]
	v_cvt_pk_f16_f32 v5, v4, v5
	v_cvt_pk_f16_f32 v4, v2, v3
	v_cvt_pk_f16_f32 v3, v8, v9
	v_cvt_pk_f16_f32 v2, v6, v7
	global_store_dwordx4 v[242:243], v[2:5], off offset:64
	s_mov_b64 s[0:1], -1
	s_and_b64 vcc, exec, s[2:3]
	s_cbranch_vccnz .LBB0_1225
	s_andn2_b64 vcc, exec, s[8:9]
	s_cbranch_vccnz .LBB0_1224
	s_barrier
	s_branch .LBB0_1224

.LBB0_2092:
	v_lshl_or_b32 v130, s74, 8, v177
	v_lshl_add_u32 v162, s73, 8, v1
	v_ashrrev_i32_e32 v131, 31, v130
	v_lshlrev_b64 v[164:165], 1, v[130:131]
	v_or_b32_e32 v130, 16, v162
	v_ashrrev_i32_e32 v163, 31, v162
	v_ashrrev_i32_e32 v131, 31, v130
	v_lshlrev_b64 v[132:133], 12, v[162:163]
	v_lshlrev_b64 v[130:131], 12, v[130:131]
	v_lshl_add_u64 v[132:133], s[64:65], 0, v[132:133]
	v_lshl_add_u64 v[130:131], s[64:65], 0, v[130:131]
	v_lshl_add_u64 v[174:175], v[132:133], 0, v[164:165]
	v_lshl_add_u64 v[172:173], v[130:131], 0, v[164:165]
	v_mov_b32_e32 v209, 0
	v_mov_b32_e32 v208, 0x10000
	v_lshl_add_u64 v[194:195], v[208:209], 0, v[174:175]
	v_mov_b32_e32 v208, 0x20000
	v_lshl_add_u64 v[196:197], v[208:209], 0, v[174:175]
	v_mov_b32_e32 v208, 0x30000
	v_lshl_add_u64 v[198:199], v[208:209], 0, v[174:175]
	v_mov_b32_e32 v208, 0x80000
	v_lshl_add_u64 v[200:201], v[208:209], 0, v[174:175]
	v_mov_b32_e32 v208, 0x90000
	v_lshl_add_u64 v[202:203], v[208:209], 0, v[174:175]
	v_mov_b32_e32 v208, 0xa0000
	v_lshl_add_u64 v[204:205], v[208:209], 0, v[174:175]
	v_mov_b32_e32 v208, 0xb0000
	v_lshl_add_u64 v[206:207], v[208:209], 0, v[174:175]
	global_load_dwordx4 v[130:133], v[174:175], off
	global_load_dwordx4 v[134:137], v[174:175], off offset:64
	global_load_dwordx4 v[138:141], v[194:195], off
	global_load_dwordx4 v[142:145], v[194:195], off offset:64
	global_load_dwordx4 v[162:165], v[196:197], off
	global_load_dwordx4 v[166:169], v[196:197], off offset:64
	global_load_dwordx4 v[170:173], v[198:199], off
	global_load_dwordx4 v[182:185], v[198:199], off offset:64
	s_waitcnt vmcnt(7)
	v_cvt_f32_f16_e32 v186, v130
	v_cvt_f32_f16_sdwa v187, v130 dst_sel:DWORD dst_unused:UNUSED_PAD src0_sel:WORD_1
	v_cvt_f32_f16_e32 v188, v131
	v_cvt_f32_f16_sdwa v189, v131 dst_sel:DWORD dst_unused:UNUSED_PAD src0_sel:WORD_1
	v_cvt_f32_f16_e32 v190, v132
	v_cvt_f32_f16_sdwa v191, v132 dst_sel:DWORD dst_unused:UNUSED_PAD src0_sel:WORD_1
	v_cvt_f32_f16_e32 v192, v133
	v_cvt_f32_f16_sdwa v193, v133 dst_sel:DWORD dst_unused:UNUSED_PAD src0_sel:WORD_1
	global_load_dwordx4 v[130:133], v[200:201], off
	v_pk_fma_f32 v[126:127], v[126:127], 0.5, v[186:187] op_sel_hi:[1,0,1]
	v_pk_fma_f32 v[128:129], v[128:129], 0.5, v[188:189] op_sel_hi:[1,0,1]
	v_pk_fma_f32 v[122:123], v[122:123], 0.5, v[190:191] op_sel_hi:[1,0,1]
	v_pk_fma_f32 v[124:125], v[124:125], 0.5, v[192:193] op_sel_hi:[1,0,1]
	v_cvt_pk_f16_f32 v125, v124, v125
	v_cvt_pk_f16_f32 v124, v122, v123
	v_cvt_pk_f16_f32 v123, v128, v129
	v_cvt_pk_f16_f32 v122, v126, v127
	global_store_dwordx4 v[174:175], v[122:125], off
	s_waitcnt vmcnt(8)
	v_cvt_f32_f16_e32 v186, v134
	v_cvt_f32_f16_sdwa v187, v134 dst_sel:DWORD dst_unused:UNUSED_PAD src0_sel:WORD_1
	v_cvt_f32_f16_e32 v188, v135
	v_cvt_f32_f16_sdwa v189, v135 dst_sel:DWORD dst_unused:UNUSED_PAD src0_sel:WORD_1
	v_cvt_f32_f16_e32 v190, v136
	v_cvt_f32_f16_sdwa v191, v136 dst_sel:DWORD dst_unused:UNUSED_PAD src0_sel:WORD_1
	v_cvt_f32_f16_e32 v192, v137
	v_cvt_f32_f16_sdwa v193, v137 dst_sel:DWORD dst_unused:UNUSED_PAD src0_sel:WORD_1
	global_load_dwordx4 v[134:137], v[200:201], off offset:64
	v_pk_fma_f32 v[118:119], v[118:119], 0.5, v[186:187] op_sel_hi:[1,0,1]
	v_pk_fma_f32 v[120:121], v[120:121], 0.5, v[188:189] op_sel_hi:[1,0,1]
	v_pk_fma_f32 v[114:115], v[114:115], 0.5, v[190:191] op_sel_hi:[1,0,1]
	v_pk_fma_f32 v[116:117], v[116:117], 0.5, v[192:193] op_sel_hi:[1,0,1]
	v_cvt_pk_f16_f32 v117, v116, v117
	v_cvt_pk_f16_f32 v116, v114, v115
	v_cvt_pk_f16_f32 v115, v120, v121
	v_cvt_pk_f16_f32 v114, v118, v119
	global_store_dwordx4 v[174:175], v[114:117], off offset:64
	s_waitcnt vmcnt(9)
	v_cvt_f32_f16_e32 v186, v138
	v_cvt_f32_f16_sdwa v187, v138 dst_sel:DWORD dst_unused:UNUSED_PAD src0_sel:WORD_1
	v_cvt_f32_f16_e32 v188, v139
	v_cvt_f32_f16_sdwa v189, v139 dst_sel:DWORD dst_unused:UNUSED_PAD src0_sel:WORD_1
	v_cvt_f32_f16_e32 v190, v140
	v_cvt_f32_f16_sdwa v191, v140 dst_sel:DWORD dst_unused:UNUSED_PAD src0_sel:WORD_1
	v_cvt_f32_f16_e32 v192, v141
	v_cvt_f32_f16_sdwa v193, v141 dst_sel:DWORD dst_unused:UNUSED_PAD src0_sel:WORD_1
	global_load_dwordx4 v[138:141], v[202:203], off
	v_pk_fma_f32 v[110:111], v[110:111], 0.5, v[186:187] op_sel_hi:[1,0,1]
	v_pk_fma_f32 v[112:113], v[112:113], 0.5, v[188:189] op_sel_hi:[1,0,1]
	v_pk_fma_f32 v[106:107], v[106:107], 0.5, v[190:191] op_sel_hi:[1,0,1]
	v_pk_fma_f32 v[108:109], v[108:109], 0.5, v[192:193] op_sel_hi:[1,0,1]
	v_cvt_pk_f16_f32 v109, v108, v109
	v_cvt_pk_f16_f32 v108, v106, v107
	v_cvt_pk_f16_f32 v107, v112, v113
	v_cvt_pk_f16_f32 v106, v110, v111
	global_store_dwordx4 v[194:195], v[106:109], off
	s_waitcnt vmcnt(10)
	v_cvt_f32_f16_e32 v186, v142
	v_cvt_f32_f16_sdwa v187, v142 dst_sel:DWORD dst_unused:UNUSED_PAD src0_sel:WORD_1
	v_cvt_f32_f16_e32 v188, v143
	v_cvt_f32_f16_sdwa v189, v143 dst_sel:DWORD dst_unused:UNUSED_PAD src0_sel:WORD_1
	v_cvt_f32_f16_e32 v190, v144
	v_cvt_f32_f16_sdwa v191, v144 dst_sel:DWORD dst_unused:UNUSED_PAD src0_sel:WORD_1
	v_cvt_f32_f16_e32 v192, v145
	v_cvt_f32_f16_sdwa v193, v145 dst_sel:DWORD dst_unused:UNUSED_PAD src0_sel:WORD_1
	global_load_dwordx4 v[142:145], v[202:203], off offset:64
	v_pk_fma_f32 v[102:103], v[102:103], 0.5, v[186:187] op_sel_hi:[1,0,1]
	v_pk_fma_f32 v[104:105], v[104:105], 0.5, v[188:189] op_sel_hi:[1,0,1]
	v_pk_fma_f32 v[98:99], v[98:99], 0.5, v[190:191] op_sel_hi:[1,0,1]
	v_pk_fma_f32 v[100:101], v[100:101], 0.5, v[192:193] op_sel_hi:[1,0,1]
	v_cvt_pk_f16_f32 v101, v100, v101
	v_cvt_pk_f16_f32 v100, v98, v99
	v_cvt_pk_f16_f32 v99, v104, v105
	v_cvt_pk_f16_f32 v98, v102, v103
	global_store_dwordx4 v[194:195], v[98:101], off offset:64
	s_waitcnt vmcnt(11)
	v_cvt_f32_f16_e32 v186, v162
	v_cvt_f32_f16_sdwa v187, v162 dst_sel:DWORD dst_unused:UNUSED_PAD src0_sel:WORD_1
	v_cvt_f32_f16_e32 v188, v163
	v_cvt_f32_f16_sdwa v189, v163 dst_sel:DWORD dst_unused:UNUSED_PAD src0_sel:WORD_1
	v_cvt_f32_f16_e32 v190, v164
	v_cvt_f32_f16_sdwa v191, v164 dst_sel:DWORD dst_unused:UNUSED_PAD src0_sel:WORD_1
	v_cvt_f32_f16_e32 v192, v165
	v_cvt_f32_f16_sdwa v193, v165 dst_sel:DWORD dst_unused:UNUSED_PAD src0_sel:WORD_1
	global_load_dwordx4 v[162:165], v[204:205], off
	v_pk_fma_f32 v[94:95], v[94:95], 0.5, v[186:187] op_sel_hi:[1,0,1]
	v_pk_fma_f32 v[96:97], v[96:97], 0.5, v[188:189] op_sel_hi:[1,0,1]
	v_pk_fma_f32 v[90:91], v[90:91], 0.5, v[190:191] op_sel_hi:[1,0,1]
	v_pk_fma_f32 v[92:93], v[92:93], 0.5, v[192:193] op_sel_hi:[1,0,1]
	v_cvt_pk_f16_f32 v93, v92, v93
	v_cvt_pk_f16_f32 v92, v90, v91
	v_cvt_pk_f16_f32 v91, v96, v97
	v_cvt_pk_f16_f32 v90, v94, v95
	global_store_dwordx4 v[196:197], v[90:93], off
	s_waitcnt vmcnt(12)
	v_cvt_f32_f16_e32 v186, v166
	v_cvt_f32_f16_sdwa v187, v166 dst_sel:DWORD dst_unused:UNUSED_PAD src0_sel:WORD_1
	v_cvt_f32_f16_e32 v188, v167
	v_cvt_f32_f16_sdwa v189, v167 dst_sel:DWORD dst_unused:UNUSED_PAD src0_sel:WORD_1
	v_cvt_f32_f16_e32 v190, v168
	v_cvt_f32_f16_sdwa v191, v168 dst_sel:DWORD dst_unused:UNUSED_PAD src0_sel:WORD_1
	v_cvt_f32_f16_e32 v192, v169
	v_cvt_f32_f16_sdwa v193, v169 dst_sel:DWORD dst_unused:UNUSED_PAD src0_sel:WORD_1
	global_load_dwordx4 v[166:169], v[204:205], off offset:64
	v_pk_fma_f32 v[86:87], v[86:87], 0.5, v[186:187] op_sel_hi:[1,0,1]
	v_pk_fma_f32 v[88:89], v[88:89], 0.5, v[188:189] op_sel_hi:[1,0,1]
	v_pk_fma_f32 v[82:83], v[82:83], 0.5, v[190:191] op_sel_hi:[1,0,1]
	v_pk_fma_f32 v[84:85], v[84:85], 0.5, v[192:193] op_sel_hi:[1,0,1]
	v_cvt_pk_f16_f32 v85, v84, v85
	v_cvt_pk_f16_f32 v84, v82, v83
	v_cvt_pk_f16_f32 v83, v88, v89
	v_cvt_pk_f16_f32 v82, v86, v87
	global_store_dwordx4 v[196:197], v[82:85], off offset:64
	s_waitcnt vmcnt(13)
	v_cvt_f32_f16_e32 v186, v170
	v_cvt_f32_f16_sdwa v187, v170 dst_sel:DWORD dst_unused:UNUSED_PAD src0_sel:WORD_1
	v_cvt_f32_f16_e32 v188, v171
	v_cvt_f32_f16_sdwa v189, v171 dst_sel:DWORD dst_unused:UNUSED_PAD src0_sel:WORD_1
	v_cvt_f32_f16_e32 v190, v172
	v_cvt_f32_f16_sdwa v191, v172 dst_sel:DWORD dst_unused:UNUSED_PAD src0_sel:WORD_1
	v_cvt_f32_f16_e32 v192, v173
	v_cvt_f32_f16_sdwa v193, v173 dst_sel:DWORD dst_unused:UNUSED_PAD src0_sel:WORD_1
	global_load_dwordx4 v[170:173], v[206:207], off
	v_pk_fma_f32 v[78:79], v[78:79], 0.5, v[186:187] op_sel_hi:[1,0,1]
	v_pk_fma_f32 v[80:81], v[80:81], 0.5, v[188:189] op_sel_hi:[1,0,1]
	v_pk_fma_f32 v[74:75], v[74:75], 0.5, v[190:191] op_sel_hi:[1,0,1]
	v_pk_fma_f32 v[76:77], v[76:77], 0.5, v[192:193] op_sel_hi:[1,0,1]
	v_cvt_pk_f16_f32 v77, v76, v77
	v_cvt_pk_f16_f32 v76, v74, v75
	v_cvt_pk_f16_f32 v75, v80, v81
	v_cvt_pk_f16_f32 v74, v78, v79
	global_store_dwordx4 v[198:199], v[74:77], off
	s_waitcnt vmcnt(14)
	v_cvt_f32_f16_e32 v186, v182
	v_cvt_f32_f16_sdwa v187, v182 dst_sel:DWORD dst_unused:UNUSED_PAD src0_sel:WORD_1
	v_cvt_f32_f16_e32 v188, v183
	v_cvt_f32_f16_sdwa v189, v183 dst_sel:DWORD dst_unused:UNUSED_PAD src0_sel:WORD_1
	v_cvt_f32_f16_e32 v190, v184
	v_cvt_f32_f16_sdwa v191, v184 dst_sel:DWORD dst_unused:UNUSED_PAD src0_sel:WORD_1
	v_cvt_f32_f16_e32 v192, v185
	v_cvt_f32_f16_sdwa v193, v185 dst_sel:DWORD dst_unused:UNUSED_PAD src0_sel:WORD_1
	global_load_dwordx4 v[182:185], v[206:207], off offset:64
	v_pk_fma_f32 v[70:71], v[70:71], 0.5, v[186:187] op_sel_hi:[1,0,1]
	v_pk_fma_f32 v[72:73], v[72:73], 0.5, v[188:189] op_sel_hi:[1,0,1]
	v_pk_fma_f32 v[66:67], v[66:67], 0.5, v[190:191] op_sel_hi:[1,0,1]
	v_pk_fma_f32 v[68:69], v[68:69], 0.5, v[192:193] op_sel_hi:[1,0,1]
	v_cvt_pk_f16_f32 v69, v68, v69
	v_cvt_pk_f16_f32 v68, v66, v67
	v_cvt_pk_f16_f32 v67, v72, v73
	v_cvt_pk_f16_f32 v66, v70, v71
	global_store_dwordx4 v[198:199], v[66:69], off offset:64
	s_waitcnt vmcnt(15)
	v_cvt_f32_f16_e32 v186, v130
	v_cvt_f32_f16_sdwa v187, v130 dst_sel:DWORD dst_unused:UNUSED_PAD src0_sel:WORD_1
	v_cvt_f32_f16_e32 v188, v131
	v_cvt_f32_f16_sdwa v189, v131 dst_sel:DWORD dst_unused:UNUSED_PAD src0_sel:WORD_1
	v_cvt_f32_f16_e32 v190, v132
	v_cvt_f32_f16_sdwa v191, v132 dst_sel:DWORD dst_unused:UNUSED_PAD src0_sel:WORD_1
	v_cvt_f32_f16_e32 v192, v133
	v_cvt_f32_f16_sdwa v193, v133 dst_sel:DWORD dst_unused:UNUSED_PAD src0_sel:WORD_1
	v_pk_fma_f32 v[62:63], v[62:63], 0.5, v[186:187] op_sel_hi:[1,0,1]
	v_pk_fma_f32 v[64:65], v[64:65], 0.5, v[188:189] op_sel_hi:[1,0,1]
	v_pk_fma_f32 v[58:59], v[58:59], 0.5, v[190:191] op_sel_hi:[1,0,1]
	v_pk_fma_f32 v[60:61], v[60:61], 0.5, v[192:193] op_sel_hi:[1,0,1]
	v_cvt_pk_f16_f32 v61, v60, v61
	v_cvt_pk_f16_f32 v60, v58, v59
	v_cvt_pk_f16_f32 v59, v64, v65
	v_cvt_pk_f16_f32 v58, v62, v63
	global_store_dwordx4 v[200:201], v[58:61], off
	s_waitcnt vmcnt(14)
	v_cvt_f32_f16_e32 v186, v134
	v_cvt_f32_f16_sdwa v187, v134 dst_sel:DWORD dst_unused:UNUSED_PAD src0_sel:WORD_1
	v_cvt_f32_f16_e32 v188, v135
	v_cvt_f32_f16_sdwa v189, v135 dst_sel:DWORD dst_unused:UNUSED_PAD src0_sel:WORD_1
	v_cvt_f32_f16_e32 v190, v136
	v_cvt_f32_f16_sdwa v191, v136 dst_sel:DWORD dst_unused:UNUSED_PAD src0_sel:WORD_1
	v_cvt_f32_f16_e32 v192, v137
	v_cvt_f32_f16_sdwa v193, v137 dst_sel:DWORD dst_unused:UNUSED_PAD src0_sel:WORD_1
	v_pk_fma_f32 v[54:55], v[54:55], 0.5, v[186:187] op_sel_hi:[1,0,1]
	v_pk_fma_f32 v[56:57], v[56:57], 0.5, v[188:189] op_sel_hi:[1,0,1]
	v_pk_fma_f32 v[46:47], v[46:47], 0.5, v[190:191] op_sel_hi:[1,0,1]
	v_pk_fma_f32 v[48:49], v[48:49], 0.5, v[192:193] op_sel_hi:[1,0,1]
	v_cvt_pk_f16_f32 v49, v48, v49
	v_cvt_pk_f16_f32 v48, v46, v47
	v_cvt_pk_f16_f32 v47, v56, v57
	v_cvt_pk_f16_f32 v46, v54, v55
	global_store_dwordx4 v[200:201], v[46:49], off offset:64
	s_waitcnt vmcnt(13)
	v_cvt_f32_f16_e32 v186, v138
	v_cvt_f32_f16_sdwa v187, v138 dst_sel:DWORD dst_unused:UNUSED_PAD src0_sel:WORD_1
	v_cvt_f32_f16_e32 v188, v139
	v_cvt_f32_f16_sdwa v189, v139 dst_sel:DWORD dst_unused:UNUSED_PAD src0_sel:WORD_1
	v_cvt_f32_f16_e32 v190, v140
	v_cvt_f32_f16_sdwa v191, v140 dst_sel:DWORD dst_unused:UNUSED_PAD src0_sel:WORD_1
	v_cvt_f32_f16_e32 v192, v141
	v_cvt_f32_f16_sdwa v193, v141 dst_sel:DWORD dst_unused:UNUSED_PAD src0_sel:WORD_1
	v_pk_fma_f32 v[50:51], v[50:51], 0.5, v[186:187] op_sel_hi:[1,0,1]
	v_pk_fma_f32 v[52:53], v[52:53], 0.5, v[188:189] op_sel_hi:[1,0,1]
	v_pk_fma_f32 v[42:43], v[42:43], 0.5, v[190:191] op_sel_hi:[1,0,1]
	v_pk_fma_f32 v[44:45], v[44:45], 0.5, v[192:193] op_sel_hi:[1,0,1]
	v_cvt_pk_f16_f32 v45, v44, v45
	v_cvt_pk_f16_f32 v44, v42, v43
	v_cvt_pk_f16_f32 v43, v52, v53
	v_cvt_pk_f16_f32 v42, v50, v51
	global_store_dwordx4 v[202:203], v[42:45], off
	s_waitcnt vmcnt(12)
	v_cvt_f32_f16_e32 v186, v142
	v_cvt_f32_f16_sdwa v187, v142 dst_sel:DWORD dst_unused:UNUSED_PAD src0_sel:WORD_1
	v_cvt_f32_f16_e32 v188, v143
	v_cvt_f32_f16_sdwa v189, v143 dst_sel:DWORD dst_unused:UNUSED_PAD src0_sel:WORD_1
	v_cvt_f32_f16_e32 v190, v144
	v_cvt_f32_f16_sdwa v191, v144 dst_sel:DWORD dst_unused:UNUSED_PAD src0_sel:WORD_1
	v_cvt_f32_f16_e32 v192, v145
	v_cvt_f32_f16_sdwa v193, v145 dst_sel:DWORD dst_unused:UNUSED_PAD src0_sel:WORD_1
	v_pk_fma_f32 v[30:31], v[30:31], 0.5, v[186:187] op_sel_hi:[1,0,1]
	v_pk_fma_f32 v[32:33], v[32:33], 0.5, v[188:189] op_sel_hi:[1,0,1]
	v_pk_fma_f32 v[26:27], v[26:27], 0.5, v[190:191] op_sel_hi:[1,0,1]
	v_pk_fma_f32 v[28:29], v[28:29], 0.5, v[192:193] op_sel_hi:[1,0,1]
	v_cvt_pk_f16_f32 v29, v28, v29
	v_cvt_pk_f16_f32 v28, v26, v27
	v_cvt_pk_f16_f32 v27, v32, v33
	v_cvt_pk_f16_f32 v26, v30, v31
	global_store_dwordx4 v[202:203], v[26:29], off offset:64
	s_waitcnt vmcnt(11)
	v_cvt_f32_f16_e32 v186, v162
	v_cvt_f32_f16_sdwa v187, v162 dst_sel:DWORD dst_unused:UNUSED_PAD src0_sel:WORD_1
	v_cvt_f32_f16_e32 v188, v163
	v_cvt_f32_f16_sdwa v189, v163 dst_sel:DWORD dst_unused:UNUSED_PAD src0_sel:WORD_1
	v_cvt_f32_f16_e32 v190, v164
	v_cvt_f32_f16_sdwa v191, v164 dst_sel:DWORD dst_unused:UNUSED_PAD src0_sel:WORD_1
	v_cvt_f32_f16_e32 v192, v165
	v_cvt_f32_f16_sdwa v193, v165 dst_sel:DWORD dst_unused:UNUSED_PAD src0_sel:WORD_1
	v_pk_fma_f32 v[38:39], v[38:39], 0.5, v[186:187] op_sel_hi:[1,0,1]
	v_pk_fma_f32 v[40:41], v[40:41], 0.5, v[188:189] op_sel_hi:[1,0,1]
	v_pk_fma_f32 v[34:35], v[34:35], 0.5, v[190:191] op_sel_hi:[1,0,1]
	v_pk_fma_f32 v[36:37], v[36:37], 0.5, v[192:193] op_sel_hi:[1,0,1]
	v_cvt_pk_f16_f32 v37, v36, v37
	v_cvt_pk_f16_f32 v36, v34, v35
	v_cvt_pk_f16_f32 v35, v40, v41
	v_cvt_pk_f16_f32 v34, v38, v39
	global_store_dwordx4 v[204:205], v[34:37], off
	s_waitcnt vmcnt(10)
	v_cvt_f32_f16_e32 v186, v166
	v_cvt_f32_f16_sdwa v187, v166 dst_sel:DWORD dst_unused:UNUSED_PAD src0_sel:WORD_1
	v_cvt_f32_f16_e32 v188, v167
	v_cvt_f32_f16_sdwa v189, v167 dst_sel:DWORD dst_unused:UNUSED_PAD src0_sel:WORD_1
	v_cvt_f32_f16_e32 v190, v168
	v_cvt_f32_f16_sdwa v191, v168 dst_sel:DWORD dst_unused:UNUSED_PAD src0_sel:WORD_1
	v_cvt_f32_f16_e32 v192, v169
	v_cvt_f32_f16_sdwa v193, v169 dst_sel:DWORD dst_unused:UNUSED_PAD src0_sel:WORD_1
	v_pk_fma_f32 v[22:23], v[22:23], 0.5, v[186:187] op_sel_hi:[1,0,1]
	v_pk_fma_f32 v[24:25], v[24:25], 0.5, v[188:189] op_sel_hi:[1,0,1]
	v_pk_fma_f32 v[18:19], v[18:19], 0.5, v[190:191] op_sel_hi:[1,0,1]
	v_pk_fma_f32 v[20:21], v[20:21], 0.5, v[192:193] op_sel_hi:[1,0,1]
	v_cvt_pk_f16_f32 v21, v20, v21
	v_cvt_pk_f16_f32 v20, v18, v19
	v_cvt_pk_f16_f32 v19, v24, v25
	v_cvt_pk_f16_f32 v18, v22, v23
	global_store_dwordx4 v[204:205], v[18:21], off offset:64
	s_waitcnt vmcnt(9)
	v_cvt_f32_f16_e32 v186, v170
	v_cvt_f32_f16_sdwa v187, v170 dst_sel:DWORD dst_unused:UNUSED_PAD src0_sel:WORD_1
	v_cvt_f32_f16_e32 v188, v171
	v_cvt_f32_f16_sdwa v189, v171 dst_sel:DWORD dst_unused:UNUSED_PAD src0_sel:WORD_1
	v_cvt_f32_f16_e32 v190, v172
	v_cvt_f32_f16_sdwa v191, v172 dst_sel:DWORD dst_unused:UNUSED_PAD src0_sel:WORD_1
	v_cvt_f32_f16_e32 v192, v173
	v_cvt_f32_f16_sdwa v193, v173 dst_sel:DWORD dst_unused:UNUSED_PAD src0_sel:WORD_1
	v_pk_fma_f32 v[14:15], v[14:15], 0.5, v[186:187] op_sel_hi:[1,0,1]
	v_pk_fma_f32 v[16:17], v[16:17], 0.5, v[188:189] op_sel_hi:[1,0,1]
	v_pk_fma_f32 v[10:11], v[10:11], 0.5, v[190:191] op_sel_hi:[1,0,1]
	v_pk_fma_f32 v[12:13], v[12:13], 0.5, v[192:193] op_sel_hi:[1,0,1]
	v_cvt_pk_f16_f32 v13, v12, v13
	v_cvt_pk_f16_f32 v12, v10, v11
	v_cvt_pk_f16_f32 v11, v16, v17
	v_cvt_pk_f16_f32 v10, v14, v15
	global_store_dwordx4 v[206:207], v[10:13], off
	s_waitcnt vmcnt(8)
	v_cvt_f32_f16_e32 v186, v182
	v_cvt_f32_f16_sdwa v187, v182 dst_sel:DWORD dst_unused:UNUSED_PAD src0_sel:WORD_1
	v_cvt_f32_f16_e32 v188, v183
	v_cvt_f32_f16_sdwa v189, v183 dst_sel:DWORD dst_unused:UNUSED_PAD src0_sel:WORD_1
	v_cvt_f32_f16_e32 v190, v184
	v_cvt_f32_f16_sdwa v191, v184 dst_sel:DWORD dst_unused:UNUSED_PAD src0_sel:WORD_1
	v_cvt_f32_f16_e32 v192, v185
	v_cvt_f32_f16_sdwa v193, v185 dst_sel:DWORD dst_unused:UNUSED_PAD src0_sel:WORD_1
	v_pk_fma_f32 v[6:7], v[6:7], 0.5, v[186:187] op_sel_hi:[1,0,1]
	v_pk_fma_f32 v[8:9], v[8:9], 0.5, v[188:189] op_sel_hi:[1,0,1]
	v_pk_fma_f32 v[2:3], v[2:3], 0.5, v[190:191] op_sel_hi:[1,0,1]
	v_pk_fma_f32 v[4:5], v[4:5], 0.5, v[192:193] op_sel_hi:[1,0,1]
	v_cvt_pk_f16_f32 v5, v4, v5
	v_cvt_pk_f16_f32 v4, v2, v3
	v_cvt_pk_f16_f32 v3, v8, v9
	v_cvt_pk_f16_f32 v2, v6, v7
	global_store_dwordx4 v[206:207], v[2:5], off offset:64
	s_and_b64 vcc, exec, s[2:3]
	s_mov_b64 s[0:1], -1
	s_cbranch_vccnz .LBB0_2077
	s_andn2_b64 vcc, exec, s[8:9]
	s_cbranch_vccnz .LBB0_2076
	s_barrier
	s_branch .LBB0_2076

.LBB0_2941:
	v_lshl_or_b32 v130, s61, 8, v173
	v_lshl_add_u32 v158, s44, 8, v1
	v_ashrrev_i32_e32 v131, 31, v130
	v_lshlrev_b64 v[160:161], 1, v[130:131]
	v_or_b32_e32 v130, 16, v158
	v_ashrrev_i32_e32 v159, 31, v158
	v_ashrrev_i32_e32 v131, 31, v130
	v_lshlrev_b64 v[132:133], 12, v[158:159]
	v_lshlrev_b64 v[130:131], 12, v[130:131]
	v_lshl_add_u64 v[132:133], s[64:65], 0, v[132:133]
	v_lshl_add_u64 v[130:131], s[64:65], 0, v[130:131]
	v_lshl_add_u64 v[170:171], v[132:133], 0, v[160:161]
	v_lshl_add_u64 v[168:169], v[130:131], 0, v[160:161]
	v_mov_b32_e32 v209, 0
	v_mov_b32_e32 v208, 0x10000
	v_lshl_add_u64 v[194:195], v[208:209], 0, v[170:171]
	v_mov_b32_e32 v208, 0x20000
	v_lshl_add_u64 v[196:197], v[208:209], 0, v[170:171]
	v_mov_b32_e32 v208, 0x30000
	v_lshl_add_u64 v[198:199], v[208:209], 0, v[170:171]
	v_mov_b32_e32 v208, 0x80000
	v_lshl_add_u64 v[200:201], v[208:209], 0, v[170:171]
	v_mov_b32_e32 v208, 0x90000
	v_lshl_add_u64 v[202:203], v[208:209], 0, v[170:171]
	v_mov_b32_e32 v208, 0xa0000
	v_lshl_add_u64 v[204:205], v[208:209], 0, v[170:171]
	v_mov_b32_e32 v208, 0xb0000
	v_lshl_add_u64 v[206:207], v[208:209], 0, v[170:171]
	global_load_dwordx4 v[130:133], v[170:171], off
	global_load_dwordx4 v[134:137], v[170:171], off offset:64
	global_load_dwordx4 v[138:141], v[194:195], off
	global_load_dwordx4 v[158:161], v[194:195], off offset:64
	global_load_dwordx4 v[162:165], v[196:197], off
	global_load_dwordx4 v[166:169], v[196:197], off offset:64
	global_load_dwordx4 v[178:181], v[198:199], off
	global_load_dwordx4 v[182:185], v[198:199], off offset:64
	s_waitcnt vmcnt(7)
	v_cvt_f32_f16_e32 v186, v130
	v_cvt_f32_f16_sdwa v187, v130 dst_sel:DWORD dst_unused:UNUSED_PAD src0_sel:WORD_1
	v_cvt_f32_f16_e32 v188, v131
	v_cvt_f32_f16_sdwa v189, v131 dst_sel:DWORD dst_unused:UNUSED_PAD src0_sel:WORD_1
	v_cvt_f32_f16_e32 v190, v132
	v_cvt_f32_f16_sdwa v191, v132 dst_sel:DWORD dst_unused:UNUSED_PAD src0_sel:WORD_1
	v_cvt_f32_f16_e32 v192, v133
	v_cvt_f32_f16_sdwa v193, v133 dst_sel:DWORD dst_unused:UNUSED_PAD src0_sel:WORD_1
	global_load_dwordx4 v[130:133], v[200:201], off
	v_pk_add_f32 v[126:127], v[186:187], v[126:127]
	v_pk_add_f32 v[128:129], v[188:189], v[128:129]
	v_pk_add_f32 v[122:123], v[190:191], v[122:123]
	v_pk_add_f32 v[124:125], v[192:193], v[124:125]
	v_cvt_pk_f16_f32 v125, v124, v125
	v_cvt_pk_f16_f32 v124, v122, v123
	v_cvt_pk_f16_f32 v123, v128, v129
	v_cvt_pk_f16_f32 v122, v126, v127
	global_store_dwordx4 v[170:171], v[122:125], off
	s_waitcnt vmcnt(8)
	v_cvt_f32_f16_e32 v186, v134
	v_cvt_f32_f16_sdwa v187, v134 dst_sel:DWORD dst_unused:UNUSED_PAD src0_sel:WORD_1
	v_cvt_f32_f16_e32 v188, v135
	v_cvt_f32_f16_sdwa v189, v135 dst_sel:DWORD dst_unused:UNUSED_PAD src0_sel:WORD_1
	v_cvt_f32_f16_e32 v190, v136
	v_cvt_f32_f16_sdwa v191, v136 dst_sel:DWORD dst_unused:UNUSED_PAD src0_sel:WORD_1
	v_cvt_f32_f16_e32 v192, v137
	v_cvt_f32_f16_sdwa v193, v137 dst_sel:DWORD dst_unused:UNUSED_PAD src0_sel:WORD_1
	global_load_dwordx4 v[134:137], v[200:201], off offset:64
	v_pk_add_f32 v[118:119], v[186:187], v[118:119]
	v_pk_add_f32 v[120:121], v[188:189], v[120:121]
	v_pk_add_f32 v[114:115], v[190:191], v[114:115]
	v_pk_add_f32 v[116:117], v[192:193], v[116:117]
	v_cvt_pk_f16_f32 v117, v116, v117
	v_cvt_pk_f16_f32 v116, v114, v115
	v_cvt_pk_f16_f32 v115, v120, v121
	v_cvt_pk_f16_f32 v114, v118, v119
	global_store_dwordx4 v[170:171], v[114:117], off offset:64
	s_waitcnt vmcnt(9)
	v_cvt_f32_f16_e32 v186, v138
	v_cvt_f32_f16_sdwa v187, v138 dst_sel:DWORD dst_unused:UNUSED_PAD src0_sel:WORD_1
	v_cvt_f32_f16_e32 v188, v139
	v_cvt_f32_f16_sdwa v189, v139 dst_sel:DWORD dst_unused:UNUSED_PAD src0_sel:WORD_1
	v_cvt_f32_f16_e32 v190, v140
	v_cvt_f32_f16_sdwa v191, v140 dst_sel:DWORD dst_unused:UNUSED_PAD src0_sel:WORD_1
	v_cvt_f32_f16_e32 v192, v141
	v_cvt_f32_f16_sdwa v193, v141 dst_sel:DWORD dst_unused:UNUSED_PAD src0_sel:WORD_1
	global_load_dwordx4 v[138:141], v[202:203], off
	v_pk_add_f32 v[110:111], v[186:187], v[110:111]
	v_pk_add_f32 v[112:113], v[188:189], v[112:113]
	v_pk_add_f32 v[106:107], v[190:191], v[106:107]
	v_pk_add_f32 v[108:109], v[192:193], v[108:109]
	v_cvt_pk_f16_f32 v109, v108, v109
	v_cvt_pk_f16_f32 v108, v106, v107
	v_cvt_pk_f16_f32 v107, v112, v113
	v_cvt_pk_f16_f32 v106, v110, v111
	global_store_dwordx4 v[194:195], v[106:109], off
	s_waitcnt vmcnt(10)
	v_cvt_f32_f16_e32 v186, v158
	v_cvt_f32_f16_sdwa v187, v158 dst_sel:DWORD dst_unused:UNUSED_PAD src0_sel:WORD_1
	v_cvt_f32_f16_e32 v188, v159
	v_cvt_f32_f16_sdwa v189, v159 dst_sel:DWORD dst_unused:UNUSED_PAD src0_sel:WORD_1
	v_cvt_f32_f16_e32 v190, v160
	v_cvt_f32_f16_sdwa v191, v160 dst_sel:DWORD dst_unused:UNUSED_PAD src0_sel:WORD_1
	v_cvt_f32_f16_e32 v192, v161
	v_cvt_f32_f16_sdwa v193, v161 dst_sel:DWORD dst_unused:UNUSED_PAD src0_sel:WORD_1
	global_load_dwordx4 v[158:161], v[202:203], off offset:64
	v_pk_add_f32 v[102:103], v[186:187], v[102:103]
	v_pk_add_f32 v[104:105], v[188:189], v[104:105]
	v_pk_add_f32 v[98:99], v[190:191], v[98:99]
	v_pk_add_f32 v[100:101], v[192:193], v[100:101]
	v_cvt_pk_f16_f32 v101, v100, v101
	v_cvt_pk_f16_f32 v100, v98, v99
	v_cvt_pk_f16_f32 v99, v104, v105
	v_cvt_pk_f16_f32 v98, v102, v103
	global_store_dwordx4 v[194:195], v[98:101], off offset:64
	s_waitcnt vmcnt(11)
	v_cvt_f32_f16_e32 v186, v162
	v_cvt_f32_f16_sdwa v187, v162 dst_sel:DWORD dst_unused:UNUSED_PAD src0_sel:WORD_1
	v_cvt_f32_f16_e32 v188, v163
	v_cvt_f32_f16_sdwa v189, v163 dst_sel:DWORD dst_unused:UNUSED_PAD src0_sel:WORD_1
	v_cvt_f32_f16_e32 v190, v164
	v_cvt_f32_f16_sdwa v191, v164 dst_sel:DWORD dst_unused:UNUSED_PAD src0_sel:WORD_1
	v_cvt_f32_f16_e32 v192, v165
	v_cvt_f32_f16_sdwa v193, v165 dst_sel:DWORD dst_unused:UNUSED_PAD src0_sel:WORD_1
	global_load_dwordx4 v[162:165], v[204:205], off
	v_pk_add_f32 v[94:95], v[186:187], v[94:95]
	v_pk_add_f32 v[96:97], v[188:189], v[96:97]
	v_pk_add_f32 v[90:91], v[190:191], v[90:91]
	v_pk_add_f32 v[92:93], v[192:193], v[92:93]
	v_cvt_pk_f16_f32 v93, v92, v93
	v_cvt_pk_f16_f32 v92, v90, v91
	v_cvt_pk_f16_f32 v91, v96, v97
	v_cvt_pk_f16_f32 v90, v94, v95
	global_store_dwordx4 v[196:197], v[90:93], off
	s_waitcnt vmcnt(12)
	v_cvt_f32_f16_e32 v186, v166
	v_cvt_f32_f16_sdwa v187, v166 dst_sel:DWORD dst_unused:UNUSED_PAD src0_sel:WORD_1
	v_cvt_f32_f16_e32 v188, v167
	v_cvt_f32_f16_sdwa v189, v167 dst_sel:DWORD dst_unused:UNUSED_PAD src0_sel:WORD_1
	v_cvt_f32_f16_e32 v190, v168
	v_cvt_f32_f16_sdwa v191, v168 dst_sel:DWORD dst_unused:UNUSED_PAD src0_sel:WORD_1
	v_cvt_f32_f16_e32 v192, v169
	v_cvt_f32_f16_sdwa v193, v169 dst_sel:DWORD dst_unused:UNUSED_PAD src0_sel:WORD_1
	global_load_dwordx4 v[166:169], v[204:205], off offset:64
	v_pk_add_f32 v[86:87], v[186:187], v[86:87]
	v_pk_add_f32 v[88:89], v[188:189], v[88:89]
	v_pk_add_f32 v[82:83], v[190:191], v[82:83]
	v_pk_add_f32 v[84:85], v[192:193], v[84:85]
	v_cvt_pk_f16_f32 v85, v84, v85
	v_cvt_pk_f16_f32 v84, v82, v83
	v_cvt_pk_f16_f32 v83, v88, v89
	v_cvt_pk_f16_f32 v82, v86, v87
	global_store_dwordx4 v[196:197], v[82:85], off offset:64
	s_waitcnt vmcnt(13)
	v_cvt_f32_f16_e32 v186, v178
	v_cvt_f32_f16_sdwa v187, v178 dst_sel:DWORD dst_unused:UNUSED_PAD src0_sel:WORD_1
	v_cvt_f32_f16_e32 v188, v179
	v_cvt_f32_f16_sdwa v189, v179 dst_sel:DWORD dst_unused:UNUSED_PAD src0_sel:WORD_1
	v_cvt_f32_f16_e32 v190, v180
	v_cvt_f32_f16_sdwa v191, v180 dst_sel:DWORD dst_unused:UNUSED_PAD src0_sel:WORD_1
	v_cvt_f32_f16_e32 v192, v181
	v_cvt_f32_f16_sdwa v193, v181 dst_sel:DWORD dst_unused:UNUSED_PAD src0_sel:WORD_1
	global_load_dwordx4 v[178:181], v[206:207], off
	v_pk_add_f32 v[78:79], v[186:187], v[78:79]
	v_pk_add_f32 v[80:81], v[188:189], v[80:81]
	v_pk_add_f32 v[74:75], v[190:191], v[74:75]
	v_pk_add_f32 v[76:77], v[192:193], v[76:77]
	v_cvt_pk_f16_f32 v77, v76, v77
	v_cvt_pk_f16_f32 v76, v74, v75
	v_cvt_pk_f16_f32 v75, v80, v81
	v_cvt_pk_f16_f32 v74, v78, v79
	global_store_dwordx4 v[198:199], v[74:77], off
	s_waitcnt vmcnt(14)
	v_cvt_f32_f16_e32 v186, v182
	v_cvt_f32_f16_sdwa v187, v182 dst_sel:DWORD dst_unused:UNUSED_PAD src0_sel:WORD_1
	v_cvt_f32_f16_e32 v188, v183
	v_cvt_f32_f16_sdwa v189, v183 dst_sel:DWORD dst_unused:UNUSED_PAD src0_sel:WORD_1
	v_cvt_f32_f16_e32 v190, v184
	v_cvt_f32_f16_sdwa v191, v184 dst_sel:DWORD dst_unused:UNUSED_PAD src0_sel:WORD_1
	v_cvt_f32_f16_e32 v192, v185
	v_cvt_f32_f16_sdwa v193, v185 dst_sel:DWORD dst_unused:UNUSED_PAD src0_sel:WORD_1
	global_load_dwordx4 v[182:185], v[206:207], off offset:64
	v_pk_add_f32 v[70:71], v[186:187], v[70:71]
	v_pk_add_f32 v[72:73], v[188:189], v[72:73]
	v_pk_add_f32 v[66:67], v[190:191], v[66:67]
	v_pk_add_f32 v[68:69], v[192:193], v[68:69]
	v_cvt_pk_f16_f32 v69, v68, v69
	v_cvt_pk_f16_f32 v68, v66, v67
	v_cvt_pk_f16_f32 v67, v72, v73
	v_cvt_pk_f16_f32 v66, v70, v71
	global_store_dwordx4 v[198:199], v[66:69], off offset:64
	s_waitcnt vmcnt(15)
	v_cvt_f32_f16_e32 v186, v130
	v_cvt_f32_f16_sdwa v187, v130 dst_sel:DWORD dst_unused:UNUSED_PAD src0_sel:WORD_1
	v_cvt_f32_f16_e32 v188, v131
	v_cvt_f32_f16_sdwa v189, v131 dst_sel:DWORD dst_unused:UNUSED_PAD src0_sel:WORD_1
	v_cvt_f32_f16_e32 v190, v132
	v_cvt_f32_f16_sdwa v191, v132 dst_sel:DWORD dst_unused:UNUSED_PAD src0_sel:WORD_1
	v_cvt_f32_f16_e32 v192, v133
	v_cvt_f32_f16_sdwa v193, v133 dst_sel:DWORD dst_unused:UNUSED_PAD src0_sel:WORD_1
	v_pk_add_f32 v[62:63], v[186:187], v[62:63]
	v_pk_add_f32 v[64:65], v[188:189], v[64:65]
	v_pk_add_f32 v[58:59], v[190:191], v[58:59]
	v_pk_add_f32 v[60:61], v[192:193], v[60:61]
	v_cvt_pk_f16_f32 v61, v60, v61
	v_cvt_pk_f16_f32 v60, v58, v59
	v_cvt_pk_f16_f32 v59, v64, v65
	v_cvt_pk_f16_f32 v58, v62, v63
	global_store_dwordx4 v[200:201], v[58:61], off
	s_waitcnt vmcnt(14)
	v_cvt_f32_f16_e32 v186, v134
	v_cvt_f32_f16_sdwa v187, v134 dst_sel:DWORD dst_unused:UNUSED_PAD src0_sel:WORD_1
	v_cvt_f32_f16_e32 v188, v135
	v_cvt_f32_f16_sdwa v189, v135 dst_sel:DWORD dst_unused:UNUSED_PAD src0_sel:WORD_1
	v_cvt_f32_f16_e32 v190, v136
	v_cvt_f32_f16_sdwa v191, v136 dst_sel:DWORD dst_unused:UNUSED_PAD src0_sel:WORD_1
	v_cvt_f32_f16_e32 v192, v137
	v_cvt_f32_f16_sdwa v193, v137 dst_sel:DWORD dst_unused:UNUSED_PAD src0_sel:WORD_1
	v_pk_add_f32 v[54:55], v[186:187], v[54:55]
	v_pk_add_f32 v[56:57], v[188:189], v[56:57]
	v_pk_add_f32 v[46:47], v[190:191], v[46:47]
	v_pk_add_f32 v[48:49], v[192:193], v[48:49]
	v_cvt_pk_f16_f32 v49, v48, v49
	v_cvt_pk_f16_f32 v48, v46, v47
	v_cvt_pk_f16_f32 v47, v56, v57
	v_cvt_pk_f16_f32 v46, v54, v55
	global_store_dwordx4 v[200:201], v[46:49], off offset:64
	s_waitcnt vmcnt(13)
	v_cvt_f32_f16_e32 v186, v138
	v_cvt_f32_f16_sdwa v187, v138 dst_sel:DWORD dst_unused:UNUSED_PAD src0_sel:WORD_1
	v_cvt_f32_f16_e32 v188, v139
	v_cvt_f32_f16_sdwa v189, v139 dst_sel:DWORD dst_unused:UNUSED_PAD src0_sel:WORD_1
	v_cvt_f32_f16_e32 v190, v140
	v_cvt_f32_f16_sdwa v191, v140 dst_sel:DWORD dst_unused:UNUSED_PAD src0_sel:WORD_1
	v_cvt_f32_f16_e32 v192, v141
	v_cvt_f32_f16_sdwa v193, v141 dst_sel:DWORD dst_unused:UNUSED_PAD src0_sel:WORD_1
	v_pk_add_f32 v[50:51], v[186:187], v[50:51]
	v_pk_add_f32 v[52:53], v[188:189], v[52:53]
	v_pk_add_f32 v[42:43], v[190:191], v[42:43]
	v_pk_add_f32 v[44:45], v[192:193], v[44:45]
	v_cvt_pk_f16_f32 v45, v44, v45
	v_cvt_pk_f16_f32 v44, v42, v43
	v_cvt_pk_f16_f32 v43, v52, v53
	v_cvt_pk_f16_f32 v42, v50, v51
	global_store_dwordx4 v[202:203], v[42:45], off
	s_waitcnt vmcnt(12)
	v_cvt_f32_f16_e32 v186, v158
	v_cvt_f32_f16_sdwa v187, v158 dst_sel:DWORD dst_unused:UNUSED_PAD src0_sel:WORD_1
	v_cvt_f32_f16_e32 v188, v159
	v_cvt_f32_f16_sdwa v189, v159 dst_sel:DWORD dst_unused:UNUSED_PAD src0_sel:WORD_1
	v_cvt_f32_f16_e32 v190, v160
	v_cvt_f32_f16_sdwa v191, v160 dst_sel:DWORD dst_unused:UNUSED_PAD src0_sel:WORD_1
	v_cvt_f32_f16_e32 v192, v161
	v_cvt_f32_f16_sdwa v193, v161 dst_sel:DWORD dst_unused:UNUSED_PAD src0_sel:WORD_1
	v_pk_add_f32 v[30:31], v[186:187], v[30:31]
	v_pk_add_f32 v[32:33], v[188:189], v[32:33]
	v_pk_add_f32 v[26:27], v[190:191], v[26:27]
	v_pk_add_f32 v[28:29], v[192:193], v[28:29]
	v_cvt_pk_f16_f32 v29, v28, v29
	v_cvt_pk_f16_f32 v28, v26, v27
	v_cvt_pk_f16_f32 v27, v32, v33
	v_cvt_pk_f16_f32 v26, v30, v31
	global_store_dwordx4 v[202:203], v[26:29], off offset:64
	s_waitcnt vmcnt(11)
	v_cvt_f32_f16_e32 v186, v162
	v_cvt_f32_f16_sdwa v187, v162 dst_sel:DWORD dst_unused:UNUSED_PAD src0_sel:WORD_1
	v_cvt_f32_f16_e32 v188, v163
	v_cvt_f32_f16_sdwa v189, v163 dst_sel:DWORD dst_unused:UNUSED_PAD src0_sel:WORD_1
	v_cvt_f32_f16_e32 v190, v164
	v_cvt_f32_f16_sdwa v191, v164 dst_sel:DWORD dst_unused:UNUSED_PAD src0_sel:WORD_1
	v_cvt_f32_f16_e32 v192, v165
	v_cvt_f32_f16_sdwa v193, v165 dst_sel:DWORD dst_unused:UNUSED_PAD src0_sel:WORD_1
	v_pk_add_f32 v[38:39], v[186:187], v[38:39]
	v_pk_add_f32 v[40:41], v[188:189], v[40:41]
	v_pk_add_f32 v[34:35], v[190:191], v[34:35]
	v_pk_add_f32 v[36:37], v[192:193], v[36:37]
	v_cvt_pk_f16_f32 v37, v36, v37
	v_cvt_pk_f16_f32 v36, v34, v35
	v_cvt_pk_f16_f32 v35, v40, v41
	v_cvt_pk_f16_f32 v34, v38, v39
	global_store_dwordx4 v[204:205], v[34:37], off
	s_waitcnt vmcnt(10)
	v_cvt_f32_f16_e32 v186, v166
	v_cvt_f32_f16_sdwa v187, v166 dst_sel:DWORD dst_unused:UNUSED_PAD src0_sel:WORD_1
	v_cvt_f32_f16_e32 v188, v167
	v_cvt_f32_f16_sdwa v189, v167 dst_sel:DWORD dst_unused:UNUSED_PAD src0_sel:WORD_1
	v_cvt_f32_f16_e32 v190, v168
	v_cvt_f32_f16_sdwa v191, v168 dst_sel:DWORD dst_unused:UNUSED_PAD src0_sel:WORD_1
	v_cvt_f32_f16_e32 v192, v169
	v_cvt_f32_f16_sdwa v193, v169 dst_sel:DWORD dst_unused:UNUSED_PAD src0_sel:WORD_1
	v_pk_add_f32 v[22:23], v[186:187], v[22:23]
	v_pk_add_f32 v[24:25], v[188:189], v[24:25]
	v_pk_add_f32 v[18:19], v[190:191], v[18:19]
	v_pk_add_f32 v[20:21], v[192:193], v[20:21]
	v_cvt_pk_f16_f32 v21, v20, v21
	v_cvt_pk_f16_f32 v20, v18, v19
	v_cvt_pk_f16_f32 v19, v24, v25
	v_cvt_pk_f16_f32 v18, v22, v23
	global_store_dwordx4 v[204:205], v[18:21], off offset:64
	s_waitcnt vmcnt(9)
	v_cvt_f32_f16_e32 v186, v178
	v_cvt_f32_f16_sdwa v187, v178 dst_sel:DWORD dst_unused:UNUSED_PAD src0_sel:WORD_1
	v_cvt_f32_f16_e32 v188, v179
	v_cvt_f32_f16_sdwa v189, v179 dst_sel:DWORD dst_unused:UNUSED_PAD src0_sel:WORD_1
	v_cvt_f32_f16_e32 v190, v180
	v_cvt_f32_f16_sdwa v191, v180 dst_sel:DWORD dst_unused:UNUSED_PAD src0_sel:WORD_1
	v_cvt_f32_f16_e32 v192, v181
	v_cvt_f32_f16_sdwa v193, v181 dst_sel:DWORD dst_unused:UNUSED_PAD src0_sel:WORD_1
	v_pk_add_f32 v[14:15], v[186:187], v[14:15]
	v_pk_add_f32 v[16:17], v[188:189], v[16:17]
	v_pk_add_f32 v[10:11], v[190:191], v[10:11]
	v_pk_add_f32 v[12:13], v[192:193], v[12:13]
	v_cvt_pk_f16_f32 v13, v12, v13
	v_cvt_pk_f16_f32 v12, v10, v11
	v_cvt_pk_f16_f32 v11, v16, v17
	v_cvt_pk_f16_f32 v10, v14, v15
	global_store_dwordx4 v[206:207], v[10:13], off
	s_waitcnt vmcnt(8)
	v_cvt_f32_f16_e32 v186, v182
	v_cvt_f32_f16_sdwa v187, v182 dst_sel:DWORD dst_unused:UNUSED_PAD src0_sel:WORD_1
	v_cvt_f32_f16_e32 v188, v183
	v_cvt_f32_f16_sdwa v189, v183 dst_sel:DWORD dst_unused:UNUSED_PAD src0_sel:WORD_1
	v_cvt_f32_f16_e32 v190, v184
	v_cvt_f32_f16_sdwa v191, v184 dst_sel:DWORD dst_unused:UNUSED_PAD src0_sel:WORD_1
	v_cvt_f32_f16_e32 v192, v185
	v_cvt_f32_f16_sdwa v193, v185 dst_sel:DWORD dst_unused:UNUSED_PAD src0_sel:WORD_1
	v_pk_add_f32 v[6:7], v[186:187], v[6:7]
	v_pk_add_f32 v[8:9], v[188:189], v[8:9]
	v_pk_add_f32 v[2:3], v[190:191], v[2:3]
	v_pk_add_f32 v[4:5], v[192:193], v[4:5]
	v_cvt_pk_f16_f32 v5, v4, v5
	v_cvt_pk_f16_f32 v4, v2, v3
	v_cvt_pk_f16_f32 v3, v8, v9
	v_cvt_pk_f16_f32 v2, v6, v7
	global_store_dwordx4 v[206:207], v[2:5], off offset:64
	s_mov_b64 s[0:1], -1
	s_andn2_b64 vcc, exec, s[2:3]
	s_cbranch_vccnz .LBB0_2930
	s_andn2_b64 vcc, exec, s[8:9]
	s_cbranch_vccnz .LBB0_2929
	s_barrier
	s_branch .LBB0_2929

.LBB0_3183:
	v_lshl_or_b32 v130, s59, 8, v173
	v_lshl_add_u32 v158, s58, 8, v1
	v_ashrrev_i32_e32 v131, 31, v130
	v_lshlrev_b64 v[160:161], 1, v[130:131]
	v_or_b32_e32 v130, 16, v158
	v_ashrrev_i32_e32 v159, 31, v158
	v_ashrrev_i32_e32 v131, 31, v130
	v_lshlrev_b64 v[132:133], 12, v[158:159]
	v_lshlrev_b64 v[130:131], 12, v[130:131]
	v_lshl_add_u64 v[132:133], s[64:65], 0, v[132:133]
	v_lshl_add_u64 v[130:131], s[64:65], 0, v[130:131]
	v_lshl_add_u64 v[170:171], v[132:133], 0, v[160:161]
	v_lshl_add_u64 v[168:169], v[130:131], 0, v[160:161]
	v_mov_b32_e32 v209, 0
	v_mov_b32_e32 v208, 0x10000
	v_lshl_add_u64 v[194:195], v[208:209], 0, v[170:171]
	v_mov_b32_e32 v208, 0x20000
	v_lshl_add_u64 v[196:197], v[208:209], 0, v[170:171]
	v_mov_b32_e32 v208, 0x30000
	v_lshl_add_u64 v[198:199], v[208:209], 0, v[170:171]
	v_mov_b32_e32 v208, 0x80000
	v_lshl_add_u64 v[200:201], v[208:209], 0, v[170:171]
	v_mov_b32_e32 v208, 0x90000
	v_lshl_add_u64 v[202:203], v[208:209], 0, v[170:171]
	v_mov_b32_e32 v208, 0xa0000
	v_lshl_add_u64 v[204:205], v[208:209], 0, v[170:171]
	v_mov_b32_e32 v208, 0xb0000
	v_lshl_add_u64 v[206:207], v[208:209], 0, v[170:171]
	global_load_dwordx4 v[130:133], v[170:171], off
	global_load_dwordx4 v[134:137], v[170:171], off offset:64
	global_load_dwordx4 v[138:141], v[194:195], off
	global_load_dwordx4 v[158:161], v[194:195], off offset:64
	global_load_dwordx4 v[162:165], v[196:197], off
	global_load_dwordx4 v[166:169], v[196:197], off offset:64
	global_load_dwordx4 v[178:181], v[198:199], off
	global_load_dwordx4 v[182:185], v[198:199], off offset:64
	s_waitcnt vmcnt(7)
	v_cvt_f32_f16_e32 v186, v130
	v_cvt_f32_f16_sdwa v187, v130 dst_sel:DWORD dst_unused:UNUSED_PAD src0_sel:WORD_1
	v_cvt_f32_f16_e32 v188, v131
	v_cvt_f32_f16_sdwa v189, v131 dst_sel:DWORD dst_unused:UNUSED_PAD src0_sel:WORD_1
	v_cvt_f32_f16_e32 v190, v132
	v_cvt_f32_f16_sdwa v191, v132 dst_sel:DWORD dst_unused:UNUSED_PAD src0_sel:WORD_1
	v_cvt_f32_f16_e32 v192, v133
	v_cvt_f32_f16_sdwa v193, v133 dst_sel:DWORD dst_unused:UNUSED_PAD src0_sel:WORD_1
	global_load_dwordx4 v[130:133], v[200:201], off
	v_pk_fma_f32 v[126:127], v[126:127], 0.5, v[186:187] op_sel_hi:[1,0,1]
	v_pk_fma_f32 v[128:129], v[128:129], 0.5, v[188:189] op_sel_hi:[1,0,1]
	v_pk_fma_f32 v[122:123], v[122:123], 0.5, v[190:191] op_sel_hi:[1,0,1]
	v_pk_fma_f32 v[124:125], v[124:125], 0.5, v[192:193] op_sel_hi:[1,0,1]
	v_cvt_pk_f16_f32 v125, v124, v125
	v_cvt_pk_f16_f32 v124, v122, v123
	v_cvt_pk_f16_f32 v123, v128, v129
	v_cvt_pk_f16_f32 v122, v126, v127
	global_store_dwordx4 v[170:171], v[122:125], off
	s_waitcnt vmcnt(8)
	v_cvt_f32_f16_e32 v186, v134
	v_cvt_f32_f16_sdwa v187, v134 dst_sel:DWORD dst_unused:UNUSED_PAD src0_sel:WORD_1
	v_cvt_f32_f16_e32 v188, v135
	v_cvt_f32_f16_sdwa v189, v135 dst_sel:DWORD dst_unused:UNUSED_PAD src0_sel:WORD_1
	v_cvt_f32_f16_e32 v190, v136
	v_cvt_f32_f16_sdwa v191, v136 dst_sel:DWORD dst_unused:UNUSED_PAD src0_sel:WORD_1
	v_cvt_f32_f16_e32 v192, v137
	v_cvt_f32_f16_sdwa v193, v137 dst_sel:DWORD dst_unused:UNUSED_PAD src0_sel:WORD_1
	global_load_dwordx4 v[134:137], v[200:201], off offset:64
	v_pk_fma_f32 v[118:119], v[118:119], 0.5, v[186:187] op_sel_hi:[1,0,1]
	v_pk_fma_f32 v[120:121], v[120:121], 0.5, v[188:189] op_sel_hi:[1,0,1]
	v_pk_fma_f32 v[114:115], v[114:115], 0.5, v[190:191] op_sel_hi:[1,0,1]
	v_pk_fma_f32 v[116:117], v[116:117], 0.5, v[192:193] op_sel_hi:[1,0,1]
	v_cvt_pk_f16_f32 v117, v116, v117
	v_cvt_pk_f16_f32 v116, v114, v115
	v_cvt_pk_f16_f32 v115, v120, v121
	v_cvt_pk_f16_f32 v114, v118, v119
	global_store_dwordx4 v[170:171], v[114:117], off offset:64
	s_waitcnt vmcnt(9)
	v_cvt_f32_f16_e32 v186, v138
	v_cvt_f32_f16_sdwa v187, v138 dst_sel:DWORD dst_unused:UNUSED_PAD src0_sel:WORD_1
	v_cvt_f32_f16_e32 v188, v139
	v_cvt_f32_f16_sdwa v189, v139 dst_sel:DWORD dst_unused:UNUSED_PAD src0_sel:WORD_1
	v_cvt_f32_f16_e32 v190, v140
	v_cvt_f32_f16_sdwa v191, v140 dst_sel:DWORD dst_unused:UNUSED_PAD src0_sel:WORD_1
	v_cvt_f32_f16_e32 v192, v141
	v_cvt_f32_f16_sdwa v193, v141 dst_sel:DWORD dst_unused:UNUSED_PAD src0_sel:WORD_1
	global_load_dwordx4 v[138:141], v[202:203], off
	v_pk_fma_f32 v[110:111], v[110:111], 0.5, v[186:187] op_sel_hi:[1,0,1]
	v_pk_fma_f32 v[112:113], v[112:113], 0.5, v[188:189] op_sel_hi:[1,0,1]
	v_pk_fma_f32 v[106:107], v[106:107], 0.5, v[190:191] op_sel_hi:[1,0,1]
	v_pk_fma_f32 v[108:109], v[108:109], 0.5, v[192:193] op_sel_hi:[1,0,1]
	v_cvt_pk_f16_f32 v109, v108, v109
	v_cvt_pk_f16_f32 v108, v106, v107
	v_cvt_pk_f16_f32 v107, v112, v113
	v_cvt_pk_f16_f32 v106, v110, v111
	global_store_dwordx4 v[194:195], v[106:109], off
	s_waitcnt vmcnt(10)
	v_cvt_f32_f16_e32 v186, v158
	v_cvt_f32_f16_sdwa v187, v158 dst_sel:DWORD dst_unused:UNUSED_PAD src0_sel:WORD_1
	v_cvt_f32_f16_e32 v188, v159
	v_cvt_f32_f16_sdwa v189, v159 dst_sel:DWORD dst_unused:UNUSED_PAD src0_sel:WORD_1
	v_cvt_f32_f16_e32 v190, v160
	v_cvt_f32_f16_sdwa v191, v160 dst_sel:DWORD dst_unused:UNUSED_PAD src0_sel:WORD_1
	v_cvt_f32_f16_e32 v192, v161
	v_cvt_f32_f16_sdwa v193, v161 dst_sel:DWORD dst_unused:UNUSED_PAD src0_sel:WORD_1
	global_load_dwordx4 v[158:161], v[202:203], off offset:64
	v_pk_fma_f32 v[102:103], v[102:103], 0.5, v[186:187] op_sel_hi:[1,0,1]
	v_pk_fma_f32 v[104:105], v[104:105], 0.5, v[188:189] op_sel_hi:[1,0,1]
	v_pk_fma_f32 v[98:99], v[98:99], 0.5, v[190:191] op_sel_hi:[1,0,1]
	v_pk_fma_f32 v[100:101], v[100:101], 0.5, v[192:193] op_sel_hi:[1,0,1]
	v_cvt_pk_f16_f32 v101, v100, v101
	v_cvt_pk_f16_f32 v100, v98, v99
	v_cvt_pk_f16_f32 v99, v104, v105
	v_cvt_pk_f16_f32 v98, v102, v103
	global_store_dwordx4 v[194:195], v[98:101], off offset:64
	s_waitcnt vmcnt(11)
	v_cvt_f32_f16_e32 v186, v162
	v_cvt_f32_f16_sdwa v187, v162 dst_sel:DWORD dst_unused:UNUSED_PAD src0_sel:WORD_1
	v_cvt_f32_f16_e32 v188, v163
	v_cvt_f32_f16_sdwa v189, v163 dst_sel:DWORD dst_unused:UNUSED_PAD src0_sel:WORD_1
	v_cvt_f32_f16_e32 v190, v164
	v_cvt_f32_f16_sdwa v191, v164 dst_sel:DWORD dst_unused:UNUSED_PAD src0_sel:WORD_1
	v_cvt_f32_f16_e32 v192, v165
	v_cvt_f32_f16_sdwa v193, v165 dst_sel:DWORD dst_unused:UNUSED_PAD src0_sel:WORD_1
	global_load_dwordx4 v[162:165], v[204:205], off
	v_pk_fma_f32 v[94:95], v[94:95], 0.5, v[186:187] op_sel_hi:[1,0,1]
	v_pk_fma_f32 v[96:97], v[96:97], 0.5, v[188:189] op_sel_hi:[1,0,1]
	v_pk_fma_f32 v[90:91], v[90:91], 0.5, v[190:191] op_sel_hi:[1,0,1]
	v_pk_fma_f32 v[92:93], v[92:93], 0.5, v[192:193] op_sel_hi:[1,0,1]
	v_cvt_pk_f16_f32 v93, v92, v93
	v_cvt_pk_f16_f32 v92, v90, v91
	v_cvt_pk_f16_f32 v91, v96, v97
	v_cvt_pk_f16_f32 v90, v94, v95
	global_store_dwordx4 v[196:197], v[90:93], off
	s_waitcnt vmcnt(12)
	v_cvt_f32_f16_e32 v186, v166
	v_cvt_f32_f16_sdwa v187, v166 dst_sel:DWORD dst_unused:UNUSED_PAD src0_sel:WORD_1
	v_cvt_f32_f16_e32 v188, v167
	v_cvt_f32_f16_sdwa v189, v167 dst_sel:DWORD dst_unused:UNUSED_PAD src0_sel:WORD_1
	v_cvt_f32_f16_e32 v190, v168
	v_cvt_f32_f16_sdwa v191, v168 dst_sel:DWORD dst_unused:UNUSED_PAD src0_sel:WORD_1
	v_cvt_f32_f16_e32 v192, v169
	v_cvt_f32_f16_sdwa v193, v169 dst_sel:DWORD dst_unused:UNUSED_PAD src0_sel:WORD_1
	global_load_dwordx4 v[166:169], v[204:205], off offset:64
	v_pk_fma_f32 v[86:87], v[86:87], 0.5, v[186:187] op_sel_hi:[1,0,1]
	v_pk_fma_f32 v[88:89], v[88:89], 0.5, v[188:189] op_sel_hi:[1,0,1]
	v_pk_fma_f32 v[82:83], v[82:83], 0.5, v[190:191] op_sel_hi:[1,0,1]
	v_pk_fma_f32 v[84:85], v[84:85], 0.5, v[192:193] op_sel_hi:[1,0,1]
	v_cvt_pk_f16_f32 v85, v84, v85
	v_cvt_pk_f16_f32 v84, v82, v83
	v_cvt_pk_f16_f32 v83, v88, v89
	v_cvt_pk_f16_f32 v82, v86, v87
	global_store_dwordx4 v[196:197], v[82:85], off offset:64
	s_waitcnt vmcnt(13)
	v_cvt_f32_f16_e32 v186, v178
	v_cvt_f32_f16_sdwa v187, v178 dst_sel:DWORD dst_unused:UNUSED_PAD src0_sel:WORD_1
	v_cvt_f32_f16_e32 v188, v179
	v_cvt_f32_f16_sdwa v189, v179 dst_sel:DWORD dst_unused:UNUSED_PAD src0_sel:WORD_1
	v_cvt_f32_f16_e32 v190, v180
	v_cvt_f32_f16_sdwa v191, v180 dst_sel:DWORD dst_unused:UNUSED_PAD src0_sel:WORD_1
	v_cvt_f32_f16_e32 v192, v181
	v_cvt_f32_f16_sdwa v193, v181 dst_sel:DWORD dst_unused:UNUSED_PAD src0_sel:WORD_1
	global_load_dwordx4 v[178:181], v[206:207], off
	v_pk_fma_f32 v[78:79], v[78:79], 0.5, v[186:187] op_sel_hi:[1,0,1]
	v_pk_fma_f32 v[80:81], v[80:81], 0.5, v[188:189] op_sel_hi:[1,0,1]
	v_pk_fma_f32 v[74:75], v[74:75], 0.5, v[190:191] op_sel_hi:[1,0,1]
	v_pk_fma_f32 v[76:77], v[76:77], 0.5, v[192:193] op_sel_hi:[1,0,1]
	v_cvt_pk_f16_f32 v77, v76, v77
	v_cvt_pk_f16_f32 v76, v74, v75
	v_cvt_pk_f16_f32 v75, v80, v81
	v_cvt_pk_f16_f32 v74, v78, v79
	global_store_dwordx4 v[198:199], v[74:77], off
	s_waitcnt vmcnt(14)
	v_cvt_f32_f16_e32 v186, v182
	v_cvt_f32_f16_sdwa v187, v182 dst_sel:DWORD dst_unused:UNUSED_PAD src0_sel:WORD_1
	v_cvt_f32_f16_e32 v188, v183
	v_cvt_f32_f16_sdwa v189, v183 dst_sel:DWORD dst_unused:UNUSED_PAD src0_sel:WORD_1
	v_cvt_f32_f16_e32 v190, v184
	v_cvt_f32_f16_sdwa v191, v184 dst_sel:DWORD dst_unused:UNUSED_PAD src0_sel:WORD_1
	v_cvt_f32_f16_e32 v192, v185
	v_cvt_f32_f16_sdwa v193, v185 dst_sel:DWORD dst_unused:UNUSED_PAD src0_sel:WORD_1
	global_load_dwordx4 v[182:185], v[206:207], off offset:64
	v_pk_fma_f32 v[70:71], v[70:71], 0.5, v[186:187] op_sel_hi:[1,0,1]
	v_pk_fma_f32 v[72:73], v[72:73], 0.5, v[188:189] op_sel_hi:[1,0,1]
	v_pk_fma_f32 v[66:67], v[66:67], 0.5, v[190:191] op_sel_hi:[1,0,1]
	v_pk_fma_f32 v[68:69], v[68:69], 0.5, v[192:193] op_sel_hi:[1,0,1]
	v_cvt_pk_f16_f32 v69, v68, v69
	v_cvt_pk_f16_f32 v68, v66, v67
	v_cvt_pk_f16_f32 v67, v72, v73
	v_cvt_pk_f16_f32 v66, v70, v71
	global_store_dwordx4 v[198:199], v[66:69], off offset:64
	s_waitcnt vmcnt(15)
	v_cvt_f32_f16_e32 v186, v130
	v_cvt_f32_f16_sdwa v187, v130 dst_sel:DWORD dst_unused:UNUSED_PAD src0_sel:WORD_1
	v_cvt_f32_f16_e32 v188, v131
	v_cvt_f32_f16_sdwa v189, v131 dst_sel:DWORD dst_unused:UNUSED_PAD src0_sel:WORD_1
	v_cvt_f32_f16_e32 v190, v132
	v_cvt_f32_f16_sdwa v191, v132 dst_sel:DWORD dst_unused:UNUSED_PAD src0_sel:WORD_1
	v_cvt_f32_f16_e32 v192, v133
	v_cvt_f32_f16_sdwa v193, v133 dst_sel:DWORD dst_unused:UNUSED_PAD src0_sel:WORD_1
	v_pk_fma_f32 v[62:63], v[62:63], 0.5, v[186:187] op_sel_hi:[1,0,1]
	v_pk_fma_f32 v[64:65], v[64:65], 0.5, v[188:189] op_sel_hi:[1,0,1]
	v_pk_fma_f32 v[58:59], v[58:59], 0.5, v[190:191] op_sel_hi:[1,0,1]
	v_pk_fma_f32 v[60:61], v[60:61], 0.5, v[192:193] op_sel_hi:[1,0,1]
	v_cvt_pk_f16_f32 v61, v60, v61
	v_cvt_pk_f16_f32 v60, v58, v59
	v_cvt_pk_f16_f32 v59, v64, v65
	v_cvt_pk_f16_f32 v58, v62, v63
	global_store_dwordx4 v[200:201], v[58:61], off
	s_waitcnt vmcnt(14)
	v_cvt_f32_f16_e32 v186, v134
	v_cvt_f32_f16_sdwa v187, v134 dst_sel:DWORD dst_unused:UNUSED_PAD src0_sel:WORD_1
	v_cvt_f32_f16_e32 v188, v135
	v_cvt_f32_f16_sdwa v189, v135 dst_sel:DWORD dst_unused:UNUSED_PAD src0_sel:WORD_1
	v_cvt_f32_f16_e32 v190, v136
	v_cvt_f32_f16_sdwa v191, v136 dst_sel:DWORD dst_unused:UNUSED_PAD src0_sel:WORD_1
	v_cvt_f32_f16_e32 v192, v137
	v_cvt_f32_f16_sdwa v193, v137 dst_sel:DWORD dst_unused:UNUSED_PAD src0_sel:WORD_1
	v_pk_fma_f32 v[54:55], v[54:55], 0.5, v[186:187] op_sel_hi:[1,0,1]
	v_pk_fma_f32 v[56:57], v[56:57], 0.5, v[188:189] op_sel_hi:[1,0,1]
	v_pk_fma_f32 v[46:47], v[46:47], 0.5, v[190:191] op_sel_hi:[1,0,1]
	v_pk_fma_f32 v[48:49], v[48:49], 0.5, v[192:193] op_sel_hi:[1,0,1]
	v_cvt_pk_f16_f32 v49, v48, v49
	v_cvt_pk_f16_f32 v48, v46, v47
	v_cvt_pk_f16_f32 v47, v56, v57
	v_cvt_pk_f16_f32 v46, v54, v55
	global_store_dwordx4 v[200:201], v[46:49], off offset:64
	s_waitcnt vmcnt(13)
	v_cvt_f32_f16_e32 v186, v138
	v_cvt_f32_f16_sdwa v187, v138 dst_sel:DWORD dst_unused:UNUSED_PAD src0_sel:WORD_1
	v_cvt_f32_f16_e32 v188, v139
	v_cvt_f32_f16_sdwa v189, v139 dst_sel:DWORD dst_unused:UNUSED_PAD src0_sel:WORD_1
	v_cvt_f32_f16_e32 v190, v140
	v_cvt_f32_f16_sdwa v191, v140 dst_sel:DWORD dst_unused:UNUSED_PAD src0_sel:WORD_1
	v_cvt_f32_f16_e32 v192, v141
	v_cvt_f32_f16_sdwa v193, v141 dst_sel:DWORD dst_unused:UNUSED_PAD src0_sel:WORD_1
	v_pk_fma_f32 v[50:51], v[50:51], 0.5, v[186:187] op_sel_hi:[1,0,1]
	v_pk_fma_f32 v[52:53], v[52:53], 0.5, v[188:189] op_sel_hi:[1,0,1]
	v_pk_fma_f32 v[42:43], v[42:43], 0.5, v[190:191] op_sel_hi:[1,0,1]
	v_pk_fma_f32 v[44:45], v[44:45], 0.5, v[192:193] op_sel_hi:[1,0,1]
	v_cvt_pk_f16_f32 v45, v44, v45
	v_cvt_pk_f16_f32 v44, v42, v43
	v_cvt_pk_f16_f32 v43, v52, v53
	v_cvt_pk_f16_f32 v42, v50, v51
	global_store_dwordx4 v[202:203], v[42:45], off
	s_waitcnt vmcnt(12)
	v_cvt_f32_f16_e32 v186, v158
	v_cvt_f32_f16_sdwa v187, v158 dst_sel:DWORD dst_unused:UNUSED_PAD src0_sel:WORD_1
	v_cvt_f32_f16_e32 v188, v159
	v_cvt_f32_f16_sdwa v189, v159 dst_sel:DWORD dst_unused:UNUSED_PAD src0_sel:WORD_1
	v_cvt_f32_f16_e32 v190, v160
	v_cvt_f32_f16_sdwa v191, v160 dst_sel:DWORD dst_unused:UNUSED_PAD src0_sel:WORD_1
	v_cvt_f32_f16_e32 v192, v161
	v_cvt_f32_f16_sdwa v193, v161 dst_sel:DWORD dst_unused:UNUSED_PAD src0_sel:WORD_1
	v_pk_fma_f32 v[30:31], v[30:31], 0.5, v[186:187] op_sel_hi:[1,0,1]
	v_pk_fma_f32 v[32:33], v[32:33], 0.5, v[188:189] op_sel_hi:[1,0,1]
	v_pk_fma_f32 v[26:27], v[26:27], 0.5, v[190:191] op_sel_hi:[1,0,1]
	v_pk_fma_f32 v[28:29], v[28:29], 0.5, v[192:193] op_sel_hi:[1,0,1]
	v_cvt_pk_f16_f32 v29, v28, v29
	v_cvt_pk_f16_f32 v28, v26, v27
	v_cvt_pk_f16_f32 v27, v32, v33
	v_cvt_pk_f16_f32 v26, v30, v31
	global_store_dwordx4 v[202:203], v[26:29], off offset:64
	s_waitcnt vmcnt(11)
	v_cvt_f32_f16_e32 v186, v162
	v_cvt_f32_f16_sdwa v187, v162 dst_sel:DWORD dst_unused:UNUSED_PAD src0_sel:WORD_1
	v_cvt_f32_f16_e32 v188, v163
	v_cvt_f32_f16_sdwa v189, v163 dst_sel:DWORD dst_unused:UNUSED_PAD src0_sel:WORD_1
	v_cvt_f32_f16_e32 v190, v164
	v_cvt_f32_f16_sdwa v191, v164 dst_sel:DWORD dst_unused:UNUSED_PAD src0_sel:WORD_1
	v_cvt_f32_f16_e32 v192, v165
	v_cvt_f32_f16_sdwa v193, v165 dst_sel:DWORD dst_unused:UNUSED_PAD src0_sel:WORD_1
	v_pk_fma_f32 v[38:39], v[38:39], 0.5, v[186:187] op_sel_hi:[1,0,1]
	v_pk_fma_f32 v[40:41], v[40:41], 0.5, v[188:189] op_sel_hi:[1,0,1]
	v_pk_fma_f32 v[34:35], v[34:35], 0.5, v[190:191] op_sel_hi:[1,0,1]
	v_pk_fma_f32 v[36:37], v[36:37], 0.5, v[192:193] op_sel_hi:[1,0,1]
	v_cvt_pk_f16_f32 v37, v36, v37
	v_cvt_pk_f16_f32 v36, v34, v35
	v_cvt_pk_f16_f32 v35, v40, v41
	v_cvt_pk_f16_f32 v34, v38, v39
	global_store_dwordx4 v[204:205], v[34:37], off
	s_waitcnt vmcnt(10)
	v_cvt_f32_f16_e32 v186, v166
	v_cvt_f32_f16_sdwa v187, v166 dst_sel:DWORD dst_unused:UNUSED_PAD src0_sel:WORD_1
	v_cvt_f32_f16_e32 v188, v167
	v_cvt_f32_f16_sdwa v189, v167 dst_sel:DWORD dst_unused:UNUSED_PAD src0_sel:WORD_1
	v_cvt_f32_f16_e32 v190, v168
	v_cvt_f32_f16_sdwa v191, v168 dst_sel:DWORD dst_unused:UNUSED_PAD src0_sel:WORD_1
	v_cvt_f32_f16_e32 v192, v169
	v_cvt_f32_f16_sdwa v193, v169 dst_sel:DWORD dst_unused:UNUSED_PAD src0_sel:WORD_1
	v_pk_fma_f32 v[22:23], v[22:23], 0.5, v[186:187] op_sel_hi:[1,0,1]
	v_pk_fma_f32 v[24:25], v[24:25], 0.5, v[188:189] op_sel_hi:[1,0,1]
	v_pk_fma_f32 v[18:19], v[18:19], 0.5, v[190:191] op_sel_hi:[1,0,1]
	v_pk_fma_f32 v[20:21], v[20:21], 0.5, v[192:193] op_sel_hi:[1,0,1]
	v_cvt_pk_f16_f32 v21, v20, v21
	v_cvt_pk_f16_f32 v20, v18, v19
	v_cvt_pk_f16_f32 v19, v24, v25
	v_cvt_pk_f16_f32 v18, v22, v23
	global_store_dwordx4 v[204:205], v[18:21], off offset:64
	s_waitcnt vmcnt(9)
	v_cvt_f32_f16_e32 v186, v178
	v_cvt_f32_f16_sdwa v187, v178 dst_sel:DWORD dst_unused:UNUSED_PAD src0_sel:WORD_1
	v_cvt_f32_f16_e32 v188, v179
	v_cvt_f32_f16_sdwa v189, v179 dst_sel:DWORD dst_unused:UNUSED_PAD src0_sel:WORD_1
	v_cvt_f32_f16_e32 v190, v180
	v_cvt_f32_f16_sdwa v191, v180 dst_sel:DWORD dst_unused:UNUSED_PAD src0_sel:WORD_1
	v_cvt_f32_f16_e32 v192, v181
	v_cvt_f32_f16_sdwa v193, v181 dst_sel:DWORD dst_unused:UNUSED_PAD src0_sel:WORD_1
	v_pk_fma_f32 v[14:15], v[14:15], 0.5, v[186:187] op_sel_hi:[1,0,1]
	v_pk_fma_f32 v[16:17], v[16:17], 0.5, v[188:189] op_sel_hi:[1,0,1]
	v_pk_fma_f32 v[10:11], v[10:11], 0.5, v[190:191] op_sel_hi:[1,0,1]
	v_pk_fma_f32 v[12:13], v[12:13], 0.5, v[192:193] op_sel_hi:[1,0,1]
	v_cvt_pk_f16_f32 v13, v12, v13
	v_cvt_pk_f16_f32 v12, v10, v11
	v_cvt_pk_f16_f32 v11, v16, v17
	v_cvt_pk_f16_f32 v10, v14, v15
	global_store_dwordx4 v[206:207], v[10:13], off
	s_waitcnt vmcnt(8)
	v_cvt_f32_f16_e32 v186, v182
	v_cvt_f32_f16_sdwa v187, v182 dst_sel:DWORD dst_unused:UNUSED_PAD src0_sel:WORD_1
	v_cvt_f32_f16_e32 v188, v183
	v_cvt_f32_f16_sdwa v189, v183 dst_sel:DWORD dst_unused:UNUSED_PAD src0_sel:WORD_1
	v_cvt_f32_f16_e32 v190, v184
	v_cvt_f32_f16_sdwa v191, v184 dst_sel:DWORD dst_unused:UNUSED_PAD src0_sel:WORD_1
	v_cvt_f32_f16_e32 v192, v185
	v_cvt_f32_f16_sdwa v193, v185 dst_sel:DWORD dst_unused:UNUSED_PAD src0_sel:WORD_1
	v_pk_fma_f32 v[6:7], v[6:7], 0.5, v[186:187] op_sel_hi:[1,0,1]
	v_pk_fma_f32 v[8:9], v[8:9], 0.5, v[188:189] op_sel_hi:[1,0,1]
	v_pk_fma_f32 v[2:3], v[2:3], 0.5, v[190:191] op_sel_hi:[1,0,1]
	v_pk_fma_f32 v[4:5], v[4:5], 0.5, v[192:193] op_sel_hi:[1,0,1]
	v_cvt_pk_f16_f32 v5, v4, v5
	v_cvt_pk_f16_f32 v4, v2, v3
	v_cvt_pk_f16_f32 v3, v8, v9
	v_cvt_pk_f16_f32 v2, v6, v7
	global_store_dwordx4 v[206:207], v[2:5], off offset:64
	s_mov_b64 s[0:1], -1
	s_and_b64 vcc, exec, s[2:3]
	s_cbranch_vccnz .LBB0_3168
	s_andn2_b64 vcc, exec, s[8:9]
	s_cbranch_vccnz .LBB0_3167
	s_barrier
	s_branch .LBB0_3167

.LBB0_3709:
	v_lshl_or_b32 v130, s57, 8, v173
	v_lshl_add_u32 v158, s40, 8, v1
	v_ashrrev_i32_e32 v131, 31, v130
	v_lshlrev_b64 v[160:161], 1, v[130:131]
	v_or_b32_e32 v130, 16, v158
	v_ashrrev_i32_e32 v159, 31, v158
	v_ashrrev_i32_e32 v131, 31, v130
	v_lshlrev_b64 v[132:133], 12, v[158:159]
	v_lshlrev_b64 v[130:131], 12, v[130:131]
	v_lshl_add_u64 v[132:133], s[64:65], 0, v[132:133]
	v_lshl_add_u64 v[130:131], s[64:65], 0, v[130:131]
	v_lshl_add_u64 v[170:171], v[132:133], 0, v[160:161]
	v_lshl_add_u64 v[168:169], v[130:131], 0, v[160:161]
	v_mov_b32_e32 v209, 0
	v_mov_b32_e32 v208, 0x10000
	v_lshl_add_u64 v[194:195], v[208:209], 0, v[170:171]
	v_mov_b32_e32 v208, 0x20000
	v_lshl_add_u64 v[196:197], v[208:209], 0, v[170:171]
	v_mov_b32_e32 v208, 0x30000
	v_lshl_add_u64 v[198:199], v[208:209], 0, v[170:171]
	v_mov_b32_e32 v208, 0x80000
	v_lshl_add_u64 v[200:201], v[208:209], 0, v[170:171]
	v_mov_b32_e32 v208, 0x90000
	v_lshl_add_u64 v[202:203], v[208:209], 0, v[170:171]
	v_mov_b32_e32 v208, 0xa0000
	v_lshl_add_u64 v[204:205], v[208:209], 0, v[170:171]
	v_mov_b32_e32 v208, 0xb0000
	v_lshl_add_u64 v[206:207], v[208:209], 0, v[170:171]
	global_load_dwordx4 v[130:133], v[170:171], off
	global_load_dwordx4 v[134:137], v[170:171], off offset:64
	global_load_dwordx4 v[138:141], v[194:195], off
	global_load_dwordx4 v[158:161], v[194:195], off offset:64
	global_load_dwordx4 v[162:165], v[196:197], off
	global_load_dwordx4 v[166:169], v[196:197], off offset:64
	global_load_dwordx4 v[178:181], v[198:199], off
	global_load_dwordx4 v[182:185], v[198:199], off offset:64
	s_waitcnt vmcnt(7)
	v_cvt_f32_f16_e32 v186, v130
	v_cvt_f32_f16_sdwa v187, v130 dst_sel:DWORD dst_unused:UNUSED_PAD src0_sel:WORD_1
	v_cvt_f32_f16_e32 v188, v131
	v_cvt_f32_f16_sdwa v189, v131 dst_sel:DWORD dst_unused:UNUSED_PAD src0_sel:WORD_1
	v_cvt_f32_f16_e32 v190, v132
	v_cvt_f32_f16_sdwa v191, v132 dst_sel:DWORD dst_unused:UNUSED_PAD src0_sel:WORD_1
	v_cvt_f32_f16_e32 v192, v133
	v_cvt_f32_f16_sdwa v193, v133 dst_sel:DWORD dst_unused:UNUSED_PAD src0_sel:WORD_1
	global_load_dwordx4 v[130:133], v[200:201], off
	v_pk_add_f32 v[126:127], v[186:187], v[126:127]
	v_pk_add_f32 v[128:129], v[188:189], v[128:129]
	v_pk_add_f32 v[122:123], v[190:191], v[122:123]
	v_pk_add_f32 v[124:125], v[192:193], v[124:125]
	v_cvt_pk_f16_f32 v125, v124, v125
	v_cvt_pk_f16_f32 v124, v122, v123
	v_cvt_pk_f16_f32 v123, v128, v129
	v_cvt_pk_f16_f32 v122, v126, v127
	global_store_dwordx4 v[170:171], v[122:125], off
	s_waitcnt vmcnt(8)
	v_cvt_f32_f16_e32 v186, v134
	v_cvt_f32_f16_sdwa v187, v134 dst_sel:DWORD dst_unused:UNUSED_PAD src0_sel:WORD_1
	v_cvt_f32_f16_e32 v188, v135
	v_cvt_f32_f16_sdwa v189, v135 dst_sel:DWORD dst_unused:UNUSED_PAD src0_sel:WORD_1
	v_cvt_f32_f16_e32 v190, v136
	v_cvt_f32_f16_sdwa v191, v136 dst_sel:DWORD dst_unused:UNUSED_PAD src0_sel:WORD_1
	v_cvt_f32_f16_e32 v192, v137
	v_cvt_f32_f16_sdwa v193, v137 dst_sel:DWORD dst_unused:UNUSED_PAD src0_sel:WORD_1
	global_load_dwordx4 v[134:137], v[200:201], off offset:64
	v_pk_add_f32 v[118:119], v[186:187], v[118:119]
	v_pk_add_f32 v[120:121], v[188:189], v[120:121]
	v_pk_add_f32 v[114:115], v[190:191], v[114:115]
	v_pk_add_f32 v[116:117], v[192:193], v[116:117]
	v_cvt_pk_f16_f32 v117, v116, v117
	v_cvt_pk_f16_f32 v116, v114, v115
	v_cvt_pk_f16_f32 v115, v120, v121
	v_cvt_pk_f16_f32 v114, v118, v119
	global_store_dwordx4 v[170:171], v[114:117], off offset:64
	s_waitcnt vmcnt(9)
	v_cvt_f32_f16_e32 v186, v138
	v_cvt_f32_f16_sdwa v187, v138 dst_sel:DWORD dst_unused:UNUSED_PAD src0_sel:WORD_1
	v_cvt_f32_f16_e32 v188, v139
	v_cvt_f32_f16_sdwa v189, v139 dst_sel:DWORD dst_unused:UNUSED_PAD src0_sel:WORD_1
	v_cvt_f32_f16_e32 v190, v140
	v_cvt_f32_f16_sdwa v191, v140 dst_sel:DWORD dst_unused:UNUSED_PAD src0_sel:WORD_1
	v_cvt_f32_f16_e32 v192, v141
	v_cvt_f32_f16_sdwa v193, v141 dst_sel:DWORD dst_unused:UNUSED_PAD src0_sel:WORD_1
	global_load_dwordx4 v[138:141], v[202:203], off
	v_pk_add_f32 v[110:111], v[186:187], v[110:111]
	v_pk_add_f32 v[112:113], v[188:189], v[112:113]
	v_pk_add_f32 v[106:107], v[190:191], v[106:107]
	v_pk_add_f32 v[108:109], v[192:193], v[108:109]
	v_cvt_pk_f16_f32 v109, v108, v109
	v_cvt_pk_f16_f32 v108, v106, v107
	v_cvt_pk_f16_f32 v107, v112, v113
	v_cvt_pk_f16_f32 v106, v110, v111
	global_store_dwordx4 v[194:195], v[106:109], off
	s_waitcnt vmcnt(10)
	v_cvt_f32_f16_e32 v186, v158
	v_cvt_f32_f16_sdwa v187, v158 dst_sel:DWORD dst_unused:UNUSED_PAD src0_sel:WORD_1
	v_cvt_f32_f16_e32 v188, v159
	v_cvt_f32_f16_sdwa v189, v159 dst_sel:DWORD dst_unused:UNUSED_PAD src0_sel:WORD_1
	v_cvt_f32_f16_e32 v190, v160
	v_cvt_f32_f16_sdwa v191, v160 dst_sel:DWORD dst_unused:UNUSED_PAD src0_sel:WORD_1
	v_cvt_f32_f16_e32 v192, v161
	v_cvt_f32_f16_sdwa v193, v161 dst_sel:DWORD dst_unused:UNUSED_PAD src0_sel:WORD_1
	global_load_dwordx4 v[158:161], v[202:203], off offset:64
	v_pk_add_f32 v[102:103], v[186:187], v[102:103]
	v_pk_add_f32 v[104:105], v[188:189], v[104:105]
	v_pk_add_f32 v[98:99], v[190:191], v[98:99]
	v_pk_add_f32 v[100:101], v[192:193], v[100:101]
	v_cvt_pk_f16_f32 v101, v100, v101
	v_cvt_pk_f16_f32 v100, v98, v99
	v_cvt_pk_f16_f32 v99, v104, v105
	v_cvt_pk_f16_f32 v98, v102, v103
	global_store_dwordx4 v[194:195], v[98:101], off offset:64
	s_waitcnt vmcnt(11)
	v_cvt_f32_f16_e32 v186, v162
	v_cvt_f32_f16_sdwa v187, v162 dst_sel:DWORD dst_unused:UNUSED_PAD src0_sel:WORD_1
	v_cvt_f32_f16_e32 v188, v163
	v_cvt_f32_f16_sdwa v189, v163 dst_sel:DWORD dst_unused:UNUSED_PAD src0_sel:WORD_1
	v_cvt_f32_f16_e32 v190, v164
	v_cvt_f32_f16_sdwa v191, v164 dst_sel:DWORD dst_unused:UNUSED_PAD src0_sel:WORD_1
	v_cvt_f32_f16_e32 v192, v165
	v_cvt_f32_f16_sdwa v193, v165 dst_sel:DWORD dst_unused:UNUSED_PAD src0_sel:WORD_1
	global_load_dwordx4 v[162:165], v[204:205], off
	v_pk_add_f32 v[94:95], v[186:187], v[94:95]
	v_pk_add_f32 v[96:97], v[188:189], v[96:97]
	v_pk_add_f32 v[90:91], v[190:191], v[90:91]
	v_pk_add_f32 v[92:93], v[192:193], v[92:93]
	v_cvt_pk_f16_f32 v93, v92, v93
	v_cvt_pk_f16_f32 v92, v90, v91
	v_cvt_pk_f16_f32 v91, v96, v97
	v_cvt_pk_f16_f32 v90, v94, v95
	global_store_dwordx4 v[196:197], v[90:93], off
	s_waitcnt vmcnt(12)
	v_cvt_f32_f16_e32 v186, v166
	v_cvt_f32_f16_sdwa v187, v166 dst_sel:DWORD dst_unused:UNUSED_PAD src0_sel:WORD_1
	v_cvt_f32_f16_e32 v188, v167
	v_cvt_f32_f16_sdwa v189, v167 dst_sel:DWORD dst_unused:UNUSED_PAD src0_sel:WORD_1
	v_cvt_f32_f16_e32 v190, v168
	v_cvt_f32_f16_sdwa v191, v168 dst_sel:DWORD dst_unused:UNUSED_PAD src0_sel:WORD_1
	v_cvt_f32_f16_e32 v192, v169
	v_cvt_f32_f16_sdwa v193, v169 dst_sel:DWORD dst_unused:UNUSED_PAD src0_sel:WORD_1
	global_load_dwordx4 v[166:169], v[204:205], off offset:64
	v_pk_add_f32 v[86:87], v[186:187], v[86:87]
	v_pk_add_f32 v[88:89], v[188:189], v[88:89]
	v_pk_add_f32 v[82:83], v[190:191], v[82:83]
	v_pk_add_f32 v[84:85], v[192:193], v[84:85]
	v_cvt_pk_f16_f32 v85, v84, v85
	v_cvt_pk_f16_f32 v84, v82, v83
	v_cvt_pk_f16_f32 v83, v88, v89
	v_cvt_pk_f16_f32 v82, v86, v87
	global_store_dwordx4 v[196:197], v[82:85], off offset:64
	s_waitcnt vmcnt(13)
	v_cvt_f32_f16_e32 v186, v178
	v_cvt_f32_f16_sdwa v187, v178 dst_sel:DWORD dst_unused:UNUSED_PAD src0_sel:WORD_1
	v_cvt_f32_f16_e32 v188, v179
	v_cvt_f32_f16_sdwa v189, v179 dst_sel:DWORD dst_unused:UNUSED_PAD src0_sel:WORD_1
	v_cvt_f32_f16_e32 v190, v180
	v_cvt_f32_f16_sdwa v191, v180 dst_sel:DWORD dst_unused:UNUSED_PAD src0_sel:WORD_1
	v_cvt_f32_f16_e32 v192, v181
	v_cvt_f32_f16_sdwa v193, v181 dst_sel:DWORD dst_unused:UNUSED_PAD src0_sel:WORD_1
	global_load_dwordx4 v[178:181], v[206:207], off
	v_pk_add_f32 v[78:79], v[186:187], v[78:79]
	v_pk_add_f32 v[80:81], v[188:189], v[80:81]
	v_pk_add_f32 v[74:75], v[190:191], v[74:75]
	v_pk_add_f32 v[76:77], v[192:193], v[76:77]
	v_cvt_pk_f16_f32 v77, v76, v77
	v_cvt_pk_f16_f32 v76, v74, v75
	v_cvt_pk_f16_f32 v75, v80, v81
	v_cvt_pk_f16_f32 v74, v78, v79
	global_store_dwordx4 v[198:199], v[74:77], off
	s_waitcnt vmcnt(14)
	v_cvt_f32_f16_e32 v186, v182
	v_cvt_f32_f16_sdwa v187, v182 dst_sel:DWORD dst_unused:UNUSED_PAD src0_sel:WORD_1
	v_cvt_f32_f16_e32 v188, v183
	v_cvt_f32_f16_sdwa v189, v183 dst_sel:DWORD dst_unused:UNUSED_PAD src0_sel:WORD_1
	v_cvt_f32_f16_e32 v190, v184
	v_cvt_f32_f16_sdwa v191, v184 dst_sel:DWORD dst_unused:UNUSED_PAD src0_sel:WORD_1
	v_cvt_f32_f16_e32 v192, v185
	v_cvt_f32_f16_sdwa v193, v185 dst_sel:DWORD dst_unused:UNUSED_PAD src0_sel:WORD_1
	global_load_dwordx4 v[182:185], v[206:207], off offset:64
	v_pk_add_f32 v[70:71], v[186:187], v[70:71]
	v_pk_add_f32 v[72:73], v[188:189], v[72:73]
	v_pk_add_f32 v[66:67], v[190:191], v[66:67]
	v_pk_add_f32 v[68:69], v[192:193], v[68:69]
	v_cvt_pk_f16_f32 v69, v68, v69
	v_cvt_pk_f16_f32 v68, v66, v67
	v_cvt_pk_f16_f32 v67, v72, v73
	v_cvt_pk_f16_f32 v66, v70, v71
	global_store_dwordx4 v[198:199], v[66:69], off offset:64
	s_waitcnt vmcnt(15)
	v_cvt_f32_f16_e32 v186, v130
	v_cvt_f32_f16_sdwa v187, v130 dst_sel:DWORD dst_unused:UNUSED_PAD src0_sel:WORD_1
	v_cvt_f32_f16_e32 v188, v131
	v_cvt_f32_f16_sdwa v189, v131 dst_sel:DWORD dst_unused:UNUSED_PAD src0_sel:WORD_1
	v_cvt_f32_f16_e32 v190, v132
	v_cvt_f32_f16_sdwa v191, v132 dst_sel:DWORD dst_unused:UNUSED_PAD src0_sel:WORD_1
	v_cvt_f32_f16_e32 v192, v133
	v_cvt_f32_f16_sdwa v193, v133 dst_sel:DWORD dst_unused:UNUSED_PAD src0_sel:WORD_1
	v_pk_add_f32 v[62:63], v[186:187], v[62:63]
	v_pk_add_f32 v[64:65], v[188:189], v[64:65]
	v_pk_add_f32 v[58:59], v[190:191], v[58:59]
	v_pk_add_f32 v[60:61], v[192:193], v[60:61]
	v_cvt_pk_f16_f32 v61, v60, v61
	v_cvt_pk_f16_f32 v60, v58, v59
	v_cvt_pk_f16_f32 v59, v64, v65
	v_cvt_pk_f16_f32 v58, v62, v63
	global_store_dwordx4 v[200:201], v[58:61], off
	s_waitcnt vmcnt(14)
	v_cvt_f32_f16_e32 v186, v134
	v_cvt_f32_f16_sdwa v187, v134 dst_sel:DWORD dst_unused:UNUSED_PAD src0_sel:WORD_1
	v_cvt_f32_f16_e32 v188, v135
	v_cvt_f32_f16_sdwa v189, v135 dst_sel:DWORD dst_unused:UNUSED_PAD src0_sel:WORD_1
	v_cvt_f32_f16_e32 v190, v136
	v_cvt_f32_f16_sdwa v191, v136 dst_sel:DWORD dst_unused:UNUSED_PAD src0_sel:WORD_1
	v_cvt_f32_f16_e32 v192, v137
	v_cvt_f32_f16_sdwa v193, v137 dst_sel:DWORD dst_unused:UNUSED_PAD src0_sel:WORD_1
	v_pk_add_f32 v[54:55], v[186:187], v[54:55]
	v_pk_add_f32 v[56:57], v[188:189], v[56:57]
	v_pk_add_f32 v[46:47], v[190:191], v[46:47]
	v_pk_add_f32 v[48:49], v[192:193], v[48:49]
	v_cvt_pk_f16_f32 v49, v48, v49
	v_cvt_pk_f16_f32 v48, v46, v47
	v_cvt_pk_f16_f32 v47, v56, v57
	v_cvt_pk_f16_f32 v46, v54, v55
	global_store_dwordx4 v[200:201], v[46:49], off offset:64
	s_waitcnt vmcnt(13)
	v_cvt_f32_f16_e32 v186, v138
	v_cvt_f32_f16_sdwa v187, v138 dst_sel:DWORD dst_unused:UNUSED_PAD src0_sel:WORD_1
	v_cvt_f32_f16_e32 v188, v139
	v_cvt_f32_f16_sdwa v189, v139 dst_sel:DWORD dst_unused:UNUSED_PAD src0_sel:WORD_1
	v_cvt_f32_f16_e32 v190, v140
	v_cvt_f32_f16_sdwa v191, v140 dst_sel:DWORD dst_unused:UNUSED_PAD src0_sel:WORD_1
	v_cvt_f32_f16_e32 v192, v141
	v_cvt_f32_f16_sdwa v193, v141 dst_sel:DWORD dst_unused:UNUSED_PAD src0_sel:WORD_1
	v_pk_add_f32 v[50:51], v[186:187], v[50:51]
	v_pk_add_f32 v[52:53], v[188:189], v[52:53]
	v_pk_add_f32 v[42:43], v[190:191], v[42:43]
	v_pk_add_f32 v[44:45], v[192:193], v[44:45]
	v_cvt_pk_f16_f32 v45, v44, v45
	v_cvt_pk_f16_f32 v44, v42, v43
	v_cvt_pk_f16_f32 v43, v52, v53
	v_cvt_pk_f16_f32 v42, v50, v51
	global_store_dwordx4 v[202:203], v[42:45], off
	s_waitcnt vmcnt(12)
	v_cvt_f32_f16_e32 v186, v158
	v_cvt_f32_f16_sdwa v187, v158 dst_sel:DWORD dst_unused:UNUSED_PAD src0_sel:WORD_1
	v_cvt_f32_f16_e32 v188, v159
	v_cvt_f32_f16_sdwa v189, v159 dst_sel:DWORD dst_unused:UNUSED_PAD src0_sel:WORD_1
	v_cvt_f32_f16_e32 v190, v160
	v_cvt_f32_f16_sdwa v191, v160 dst_sel:DWORD dst_unused:UNUSED_PAD src0_sel:WORD_1
	v_cvt_f32_f16_e32 v192, v161
	v_cvt_f32_f16_sdwa v193, v161 dst_sel:DWORD dst_unused:UNUSED_PAD src0_sel:WORD_1
	v_pk_add_f32 v[30:31], v[186:187], v[30:31]
	v_pk_add_f32 v[32:33], v[188:189], v[32:33]
	v_pk_add_f32 v[26:27], v[190:191], v[26:27]
	v_pk_add_f32 v[28:29], v[192:193], v[28:29]
	v_cvt_pk_f16_f32 v29, v28, v29
	v_cvt_pk_f16_f32 v28, v26, v27
	v_cvt_pk_f16_f32 v27, v32, v33
	v_cvt_pk_f16_f32 v26, v30, v31
	global_store_dwordx4 v[202:203], v[26:29], off offset:64
	s_waitcnt vmcnt(11)
	v_cvt_f32_f16_e32 v186, v162
	v_cvt_f32_f16_sdwa v187, v162 dst_sel:DWORD dst_unused:UNUSED_PAD src0_sel:WORD_1
	v_cvt_f32_f16_e32 v188, v163
	v_cvt_f32_f16_sdwa v189, v163 dst_sel:DWORD dst_unused:UNUSED_PAD src0_sel:WORD_1
	v_cvt_f32_f16_e32 v190, v164
	v_cvt_f32_f16_sdwa v191, v164 dst_sel:DWORD dst_unused:UNUSED_PAD src0_sel:WORD_1
	v_cvt_f32_f16_e32 v192, v165
	v_cvt_f32_f16_sdwa v193, v165 dst_sel:DWORD dst_unused:UNUSED_PAD src0_sel:WORD_1
	v_pk_add_f32 v[38:39], v[186:187], v[38:39]
	v_pk_add_f32 v[40:41], v[188:189], v[40:41]
	v_pk_add_f32 v[34:35], v[190:191], v[34:35]
	v_pk_add_f32 v[36:37], v[192:193], v[36:37]
	v_cvt_pk_f16_f32 v37, v36, v37
	v_cvt_pk_f16_f32 v36, v34, v35
	v_cvt_pk_f16_f32 v35, v40, v41
	v_cvt_pk_f16_f32 v34, v38, v39
	global_store_dwordx4 v[204:205], v[34:37], off
	s_waitcnt vmcnt(10)
	v_cvt_f32_f16_e32 v186, v166
	v_cvt_f32_f16_sdwa v187, v166 dst_sel:DWORD dst_unused:UNUSED_PAD src0_sel:WORD_1
	v_cvt_f32_f16_e32 v188, v167
	v_cvt_f32_f16_sdwa v189, v167 dst_sel:DWORD dst_unused:UNUSED_PAD src0_sel:WORD_1
	v_cvt_f32_f16_e32 v190, v168
	v_cvt_f32_f16_sdwa v191, v168 dst_sel:DWORD dst_unused:UNUSED_PAD src0_sel:WORD_1
	v_cvt_f32_f16_e32 v192, v169
	v_cvt_f32_f16_sdwa v193, v169 dst_sel:DWORD dst_unused:UNUSED_PAD src0_sel:WORD_1
	v_pk_add_f32 v[22:23], v[186:187], v[22:23]
	v_pk_add_f32 v[24:25], v[188:189], v[24:25]
	v_pk_add_f32 v[18:19], v[190:191], v[18:19]
	v_pk_add_f32 v[20:21], v[192:193], v[20:21]
	v_cvt_pk_f16_f32 v21, v20, v21
	v_cvt_pk_f16_f32 v20, v18, v19
	v_cvt_pk_f16_f32 v19, v24, v25
	v_cvt_pk_f16_f32 v18, v22, v23
	global_store_dwordx4 v[204:205], v[18:21], off offset:64
	s_waitcnt vmcnt(9)
	v_cvt_f32_f16_e32 v186, v178
	v_cvt_f32_f16_sdwa v187, v178 dst_sel:DWORD dst_unused:UNUSED_PAD src0_sel:WORD_1
	v_cvt_f32_f16_e32 v188, v179
	v_cvt_f32_f16_sdwa v189, v179 dst_sel:DWORD dst_unused:UNUSED_PAD src0_sel:WORD_1
	v_cvt_f32_f16_e32 v190, v180
	v_cvt_f32_f16_sdwa v191, v180 dst_sel:DWORD dst_unused:UNUSED_PAD src0_sel:WORD_1
	v_cvt_f32_f16_e32 v192, v181
	v_cvt_f32_f16_sdwa v193, v181 dst_sel:DWORD dst_unused:UNUSED_PAD src0_sel:WORD_1
	v_pk_add_f32 v[14:15], v[186:187], v[14:15]
	v_pk_add_f32 v[16:17], v[188:189], v[16:17]
	v_pk_add_f32 v[10:11], v[190:191], v[10:11]
	v_pk_add_f32 v[12:13], v[192:193], v[12:13]
	v_cvt_pk_f16_f32 v13, v12, v13
	v_cvt_pk_f16_f32 v12, v10, v11
	v_cvt_pk_f16_f32 v11, v16, v17
	v_cvt_pk_f16_f32 v10, v14, v15
	global_store_dwordx4 v[206:207], v[10:13], off
	s_waitcnt vmcnt(8)
	v_cvt_f32_f16_e32 v186, v182
	v_cvt_f32_f16_sdwa v187, v182 dst_sel:DWORD dst_unused:UNUSED_PAD src0_sel:WORD_1
	v_cvt_f32_f16_e32 v188, v183
	v_cvt_f32_f16_sdwa v189, v183 dst_sel:DWORD dst_unused:UNUSED_PAD src0_sel:WORD_1
	v_cvt_f32_f16_e32 v190, v184
	v_cvt_f32_f16_sdwa v191, v184 dst_sel:DWORD dst_unused:UNUSED_PAD src0_sel:WORD_1
	v_cvt_f32_f16_e32 v192, v185
	v_cvt_f32_f16_sdwa v193, v185 dst_sel:DWORD dst_unused:UNUSED_PAD src0_sel:WORD_1
	v_pk_add_f32 v[6:7], v[186:187], v[6:7]
	v_pk_add_f32 v[8:9], v[188:189], v[8:9]
	v_pk_add_f32 v[2:3], v[190:191], v[2:3]
	v_pk_add_f32 v[4:5], v[192:193], v[4:5]
	v_cvt_pk_f16_f32 v5, v4, v5
	v_cvt_pk_f16_f32 v4, v2, v3
	v_cvt_pk_f16_f32 v3, v8, v9
	v_cvt_pk_f16_f32 v2, v6, v7
	global_store_dwordx4 v[206:207], v[2:5], off offset:64
	s_mov_b64 s[0:1], -1
	s_andn2_b64 vcc, exec, s[2:3]
	s_cbranch_vccnz .LBB0_3698
	s_andn2_b64 vcc, exec, s[8:9]
	s_cbranch_vccnz .LBB0_3697
	s_barrier
	s_branch .LBB0_3697
